# out-projection residual epilogue: all 16 residual loads of a unit issued together into free registers, counted waits per use
# baseline (speedup 1.0000x reference)
; #define PG8_LAS __attribute__((address_space(3)))
; __device__ __forceinline__ u32x4 pack8(f32x4 v0, f32x4 v1) { u32x4 w; w.x = cvt_pk_bf16(v0[0], v0[1]); w.y = cvt_pk_bf16(v0[2], v0[3]); w.z = cvt_pk_bf16(v1[0], v1[1]); w.w = cvt_pk_bf16(v1[2], v1[3]); return w; }
;     __device__ __forceinline__ void operator()(const f32x4 (&acc)[2][2][4][2], const Unit& u, int wr, int wc, int fr, int fq) const {
;     ...
;             bf16_t* xbb = XB + ((size_t)(u.pm * 16 + wr * 4) * 64 + u.pn * 8 + 2 * wc) * 512 + fr * 32 + (((fq * 16) ^ ((fr >> 3) << 5)) >> 1);
;             PG8_LAS float* PL = (PG8_LAS float*)xl;
; #pragma unroll
;             for (int ai = 0; ai < 2; ++ai) {
;                 u32x4 old[4][2];
; #pragma unroll
;                 for (int m = 0; m < 4; ++m)
; #pragma unroll
;                     for (int bj = 0; bj < 2; ++bj) old[m][bj] = *(const u32x4*)(xbb + ((size_t)(ai * 8 + m) * 64 + bj) * 512);
; #pragma unroll
;                 for (int m = 0; m < 4; ++m) { const int rl = ai * HALF + wr * 64 + m * 16 + fr; bf16_t* rowp = xbb + (size_t)(ai * 8 + m) * 64 * 512; float q = 0.f;
; #pragma unroll
;                     for (int bj = 0; bj < 2; ++bj) { const u32x4 o = old[m][bj];
;                         f32x4 x0 = (f32x4){__uint_as_float(o.x << 16), __uint_as_float(o.x & 0xffff0000u), __uint_as_float(o.y << 16), __uint_as_float(o.y & 0xffff0000u)} + acc[ai][bj][m][0];
;                         f32x4 x1 = (f32x4){__uint_as_float(o.z << 16), __uint_as_float(o.z & 0xffff0000u), __uint_as_float(o.w << 16), __uint_as_float(o.w & 0xffff0000u)} + acc[ai][bj][m][1];
;                         q += ((x0[0] * x0[0] + x0[1] * x0[1]) + (x0[2] * x0[2] + x0[3] * x0[3])) + ((x1[0] * x1[0] + x1[1] * x1[1]) + (x1[2] * x1[2] + x1[3] * x1[3]));
;                         *(u32x4*)(rowp + bj * 512) = pack8(x0, x1); }
;                     q += __shfl_xor(q, 16); q += __shfl_xor(q, 32);
;                     if (fq == 0) PL[rl * 4 + wc] = q; } }
.LBB0_494:
	s_lshl_b32 s2, s2, 4
	s_add_i32 s2, s2, s66
	s_ashr_i32 s3, s2, 31
	s_lshl_b32 s37, s10, 3
	s_lshl_b64 s[2:3], s[2:3], 6
	s_ashr_i32 s39, s37, 31
	s_add_u32 s2, s2, s37
	s_addc_u32 s3, s3, s39
	s_or_b64 s[2:3], s[2:3], s[20:21]
	s_lshl_b64 s[2:3], s[2:3], 10
	v_lshl_add_u64 v[162:163], v[156:157], 0, s[2:3]
	global_load_dwordx4 v[174:177], v[162:163], off
	global_load_dwordx4 v[178:181], v[162:163], off offset:1024
	s_mov_b32 s2, 0x10000
	v_add_co_u32_e32 v114, vcc, s2, v162
	s_mov_b32 s2, 0x30000
	s_nop 0
	v_addc_co_u32_e32 v115, vcc, 0, v163, vcc
	global_load_dwordx4 v[150:153], v[114:115], off
	global_load_dwordx4 v[146:149], v[114:115], off offset:1024
	v_add_co_u32_e32 v114, vcc, s75, v162
	s_nop 0
	s_nop 0
	v_addc_co_u32_e32 v115, vcc, 0, v163, vcc
	global_load_dwordx4 v[142:145], v[114:115], off
	global_load_dwordx4 v[130:133], v[114:115], off offset:1024
	v_add_co_u32_e32 v114, vcc, s2, v162
	s_nop 0
	s_nop 0
	v_addc_co_u32_e32 v115, vcc, 0, v163, vcc
	global_load_dwordx4 v[126:129], v[114:115], off
	s_nop 0
	global_load_dwordx4 v[114:117], v[114:115], off offset:1024
	v_add_co_u32_e32 v226, vcc, 0x80000, v162
	s_nop 1
	v_addc_co_u32_e32 v227, vcc, 0, v163, vcc
	global_load_dwordx4 v[194:197], v[226:227], off
	global_load_dwordx4 v[198:201], v[226:227], off offset:1024
	v_add_co_u32_e32 v226, vcc, 0x90000, v162
	s_nop 1
	v_addc_co_u32_e32 v227, vcc, 0, v163, vcc
	global_load_dwordx4 v[202:205], v[226:227], off
	global_load_dwordx4 v[206:209], v[226:227], off offset:1024
	v_add_co_u32_e32 v226, vcc, 0xa0000, v162
	s_nop 1
	v_addc_co_u32_e32 v227, vcc, 0, v163, vcc
	global_load_dwordx4 v[210:213], v[226:227], off
	global_load_dwordx4 v[214:217], v[226:227], off offset:1024
	v_add_co_u32_e32 v226, vcc, 0xb0000, v162
	s_nop 1
	v_addc_co_u32_e32 v227, vcc, 0, v163, vcc
	global_load_dwordx4 v[218:221], v[226:227], off
	global_load_dwordx4 v[222:225], v[226:227], off offset:1024
	s_waitcnt vmcnt(15)
	v_lshlrev_b32_e32 v184, 16, v174
	v_and_b32_e32 v185, 0xffff0000, v174
	v_lshlrev_b32_e32 v174, 16, v175
	v_and_b32_e32 v175, 0xffff0000, v175
	v_pk_add_f32 v[140:141], v[140:141], v[174:175]
	v_pk_add_f32 v[138:139], v[138:139], v[184:185]
	v_lshlrev_b32_e32 v174, 16, v176
	v_and_b32_e32 v175, 0xffff0000, v176
	v_lshlrev_b32_e32 v176, 16, v177
	v_and_b32_e32 v177, 0xffff0000, v177
	v_pk_add_f32 v[176:177], v[136:137], v[176:177]
	v_pk_add_f32 v[136:137], v[134:135], v[174:175]
	v_mul_f32_e32 v134, v139, v139
	v_mul_f32_e32 v135, v141, v141
	v_fmac_f32_e32 v134, v138, v138
	v_fmac_f32_e32 v135, v140, v140
	v_add_f32_e32 v134, v134, v135
	v_mul_f32_e32 v135, v137, v137
	v_mul_f32_e32 v173, v177, v177
	v_fmac_f32_e32 v135, v136, v136
	v_fmac_f32_e32 v173, v176, v176
	v_add_f32_e32 v135, v135, v173
	v_add_f32_e32 v173, v134, v135
	v_cvt_pk_bf16_f32 v134, v138, v139
	v_cvt_pk_bf16_f32 v135, v140, v141
	v_cvt_pk_bf16_f32 v136, v136, v137
	v_cvt_pk_bf16_f32 v137, v176, v177
	global_store_dwordx4 v[162:163], v[134:137], off
	s_nop 1
	s_waitcnt vmcnt(15)
	v_lshlrev_b32_e32 v134, 16, v178
	v_and_b32_e32 v135, 0xffff0000, v178
	v_lshlrev_b32_e32 v136, 16, v179
	v_and_b32_e32 v137, 0xffff0000, v179
	v_pk_add_f32 v[124:125], v[124:125], v[136:137]
	v_pk_add_f32 v[122:123], v[122:123], v[134:135]
	v_lshlrev_b32_e32 v134, 16, v180
	v_and_b32_e32 v135, 0xffff0000, v180
	v_lshlrev_b32_e32 v136, 16, v181
	v_and_b32_e32 v137, 0xffff0000, v181
	v_pk_add_f32 v[136:137], v[120:121], v[136:137]
	v_pk_add_f32 v[120:121], v[118:119], v[134:135]
	v_mul_f32_e32 v118, v123, v123
	v_mul_f32_e32 v119, v125, v125
	v_fmac_f32_e32 v118, v122, v122
	v_fmac_f32_e32 v119, v124, v124
	v_add_f32_e32 v118, v118, v119
	v_mul_f32_e32 v119, v121, v121
	v_mul_f32_e32 v134, v137, v137
	v_fmac_f32_e32 v119, v120, v120
	v_fmac_f32_e32 v134, v136, v136
	v_add_f32_e32 v119, v119, v134
	v_add_f32_e32 v118, v118, v119
	v_add_f32_e32 v134, v173, v118
	v_cvt_pk_bf16_f32 v118, v122, v123
	v_cvt_pk_bf16_f32 v119, v124, v125
	v_cvt_pk_bf16_f32 v120, v120, v121
	v_cvt_pk_bf16_f32 v121, v136, v137
	global_store_dwordx4 v[162:163], v[118:121], off offset:1024
	s_nop 1
	v_and_b32_e32 v119, 64, v171
	v_xor_b32_e32 v118, 16, v171
	v_add_u32_e32 v119, 64, v119
	v_cmp_lt_i32_e32 vcc, v118, v119
	v_xor_b32_e32 v121, 32, v171
	s_nop 0
	v_cndmask_b32_e32 v118, v171, v118, vcc
	v_lshlrev_b32_e32 v118, 2, v118
	ds_bpermute_b32 v120, v118, v134
	v_cmp_lt_i32_e32 vcc, v121, v119
	s_waitcnt lgkmcnt(0)
	v_add_f32_e32 v120, v134, v120
	v_cndmask_b32_e32 v119, v171, v121, vcc
	v_lshlrev_b32_e32 v119, 2, v119
	ds_bpermute_b32 v121, v119, v120
	s_and_saveexec_b64 s[2:3], s[4:5]
	s_cbranch_execz .LBB0_496
	s_waitcnt lgkmcnt(0)
	v_add_f32_e32 v120, v120, v121
	ds_write_b32 v172, v120
; __device__ __forceinline__ u32x4 pack8(f32x4 v0, f32x4 v1) { u32x4 w; w.x = cvt_pk_bf16(v0[0], v0[1]); w.y = cvt_pk_bf16(v0[2], v0[3]); w.z = cvt_pk_bf16(v1[0], v1[1]); w.w = cvt_pk_bf16(v1[2], v1[3]); return w; }
;     __device__ __forceinline__ void operator()(const f32x4 (&acc)[2][2][4][2], const Unit& u, int wr, int wc, int fr, int fq) const {
;     ...
;                 for (int m = 0; m < 4; ++m) { const int rl = ai * HALF + wr * 64 + m * 16 + fr; bf16_t* rowp = xbb + (size_t)(ai * 8 + m) * 64 * 512; float q = 0.f;
; #pragma unroll
;                     for (int bj = 0; bj < 2; ++bj) { const u32x4 o = old[m][bj];
;                         f32x4 x0 = (f32x4){__uint_as_float(o.x << 16), __uint_as_float(o.x & 0xffff0000u), __uint_as_float(o.y << 16), __uint_as_float(o.y & 0xffff0000u)} + acc[ai][bj][m][0];
;                         f32x4 x1 = (f32x4){__uint_as_float(o.z << 16), __uint_as_float(o.z & 0xffff0000u), __uint_as_float(o.w << 16), __uint_as_float(o.w & 0xffff0000u)} + acc[ai][bj][m][1];
;                         q += ((x0[0] * x0[0] + x0[1] * x0[1]) + (x0[2] * x0[2] + x0[3] * x0[3])) + ((x1[0] * x1[0] + x1[1] * x1[1]) + (x1[2] * x1[2] + x1[3] * x1[3]));
;                         *(u32x4*)(rowp + bj * 512) = pack8(x0, x1); }
;                     q += __shfl_xor(q, 16); q += __shfl_xor(q, 32);
;                     if (fq == 0) PL[rl * 4 + wc] = q; } }
.LBB0_496:
	s_or_b64 exec, exec, s[2:3]
	s_waitcnt vmcnt(15)
	v_lshlrev_b32_e32 v124, 16, v150
	v_and_b32_e32 v125, 0xffff0000, v150
	v_lshlrev_b32_e32 v134, 16, v151
	v_and_b32_e32 v135, 0xffff0000, v151
	v_pk_add_f32 v[112:113], v[112:113], v[134:135]
	v_pk_add_f32 v[110:111], v[110:111], v[124:125]
	v_lshlrev_b32_e32 v124, 16, v152
	v_and_b32_e32 v125, 0xffff0000, v152
	v_lshlrev_b32_e32 v134, 16, v153
	v_and_b32_e32 v135, 0xffff0000, v153
	v_pk_add_f32 v[134:135], v[108:109], v[134:135]
	v_pk_add_f32 v[108:109], v[106:107], v[124:125]
	v_mul_f32_e32 v106, v111, v111
	v_mul_f32_e32 v107, v113, v113
	v_fmac_f32_e32 v106, v110, v110
	v_fmac_f32_e32 v107, v112, v112
	v_add_f32_e32 v106, v106, v107
	v_mul_f32_e32 v107, v109, v109
	v_mul_f32_e32 v124, v135, v135
	v_fmac_f32_e32 v107, v108, v108
	v_fmac_f32_e32 v124, v134, v134
	v_add_f32_e32 v107, v107, v124
	v_add_f32_e32 v124, v106, v107
	v_cvt_pk_bf16_f32 v106, v110, v111
	v_cvt_pk_bf16_f32 v107, v112, v113
	s_waitcnt vmcnt(14)
	v_lshlrev_b32_e32 v110, 16, v146
	v_and_b32_e32 v111, 0xffff0000, v146
	v_lshlrev_b32_e32 v112, 16, v147
	v_and_b32_e32 v113, 0xffff0000, v147
	v_pk_add_f32 v[104:105], v[104:105], v[112:113]
	v_pk_add_f32 v[102:103], v[102:103], v[110:111]
	v_lshlrev_b32_e32 v110, 16, v148
	v_and_b32_e32 v111, 0xffff0000, v148
	v_lshlrev_b32_e32 v112, 16, v149
	v_and_b32_e32 v113, 0xffff0000, v149
	v_pk_add_f32 v[110:111], v[98:99], v[110:111]
	v_mul_f32_e32 v98, v103, v103
	v_mul_f32_e32 v99, v105, v105
	v_pk_add_f32 v[112:113], v[100:101], v[112:113]
	v_fmac_f32_e32 v98, v102, v102
	v_fmac_f32_e32 v99, v104, v104
	v_add_f32_e32 v98, v98, v99
	v_mul_f32_e32 v99, v111, v111
	v_mul_f32_e32 v100, v113, v113
	v_fmac_f32_e32 v99, v110, v110
	v_fmac_f32_e32 v100, v112, v112
	v_add_f32_e32 v99, v99, v100
	v_add_f32_e32 v98, v98, v99
	v_add_f32_e32 v98, v124, v98
	ds_bpermute_b32 v99, v118, v98
	s_mov_b64 s[2:3], 0x10000
	s_waitcnt lgkmcnt(1)
	v_lshl_add_u64 v[120:121], v[162:163], 0, s[2:3]
	s_mov_b64 s[2:3], 0x10400
	v_lshl_add_u64 v[122:123], v[162:163], 0, s[2:3]
	s_waitcnt lgkmcnt(0)
	v_add_f32_e32 v98, v98, v99
	ds_bpermute_b32 v99, v119, v98
	v_cvt_pk_bf16_f32 v108, v108, v109
	v_cvt_pk_bf16_f32 v109, v134, v135
	global_store_dwordx4 v[120:121], v[106:109], off
	v_cvt_pk_bf16_f32 v100, v102, v103
	v_cvt_pk_bf16_f32 v101, v104, v105
	v_cvt_pk_bf16_f32 v102, v110, v111
	v_cvt_pk_bf16_f32 v103, v112, v113
	global_store_dwordx4 v[122:123], v[100:103], off
	s_and_saveexec_b64 s[2:3], s[4:5]
	s_cbranch_execz .LBB0_498
	s_waitcnt lgkmcnt(0)
	v_add_f32_e32 v98, v98, v99
	ds_write_b32 v172, v98 offset:256
.LBB0_498:
	s_or_b64 exec, exec, s[2:3]
	s_nop 0
	s_waitcnt vmcnt(15)
	v_lshlrev_b32_e32 v102, 16, v142
	v_and_b32_e32 v103, 0xffff0000, v142
	v_lshlrev_b32_e32 v104, 16, v143
	v_and_b32_e32 v105, 0xffff0000, v143
	v_pk_add_f32 v[96:97], v[96:97], v[104:105]
	v_pk_add_f32 v[94:95], v[94:95], v[102:103]
	v_lshlrev_b32_e32 v102, 16, v144
	v_and_b32_e32 v103, 0xffff0000, v144
	v_lshlrev_b32_e32 v104, 16, v145
	v_and_b32_e32 v105, 0xffff0000, v145
	v_pk_add_f32 v[104:105], v[92:93], v[104:105]
	v_pk_add_f32 v[92:93], v[90:91], v[102:103]
	v_mul_f32_e32 v90, v95, v95
	v_mul_f32_e32 v91, v97, v97
	v_fmac_f32_e32 v90, v94, v94
	v_fmac_f32_e32 v91, v96, v96
	v_add_f32_e32 v90, v90, v91
	v_mul_f32_e32 v91, v93, v93
	v_mul_f32_e32 v102, v105, v105
	v_fmac_f32_e32 v91, v92, v92
	v_fmac_f32_e32 v102, v104, v104
	v_add_f32_e32 v91, v91, v102
	v_add_f32_e32 v102, v90, v91
	v_cvt_pk_bf16_f32 v90, v94, v95
	v_cvt_pk_bf16_f32 v91, v96, v97
	s_nop 0
	s_waitcnt vmcnt(14)
	v_lshlrev_b32_e32 v94, 16, v130
	v_and_b32_e32 v95, 0xffff0000, v130
	v_lshlrev_b32_e32 v96, 16, v131
	v_and_b32_e32 v97, 0xffff0000, v131
	v_pk_add_f32 v[88:89], v[88:89], v[96:97]
	v_pk_add_f32 v[86:87], v[86:87], v[94:95]
	v_lshlrev_b32_e32 v94, 16, v132
	v_and_b32_e32 v95, 0xffff0000, v132
	v_lshlrev_b32_e32 v96, 16, v133
	v_and_b32_e32 v97, 0xffff0000, v133
	v_pk_add_f32 v[94:95], v[82:83], v[94:95]
	v_mul_f32_e32 v82, v87, v87
	v_mul_f32_e32 v83, v89, v89
	v_pk_add_f32 v[96:97], v[84:85], v[96:97]
	v_fmac_f32_e32 v82, v86, v86
	v_fmac_f32_e32 v83, v88, v88
	v_add_f32_e32 v82, v82, v83
	v_mul_f32_e32 v83, v95, v95
	v_mul_f32_e32 v84, v97, v97
	v_fmac_f32_e32 v83, v94, v94
	v_fmac_f32_e32 v84, v96, v96
	v_add_f32_e32 v83, v83, v84
	v_add_f32_e32 v82, v82, v83
	v_add_f32_e32 v82, v102, v82
	ds_bpermute_b32 v83, v118, v82
	s_mov_b64 s[2:3], 0x20000
	s_waitcnt lgkmcnt(1)
	v_lshl_add_u64 v[98:99], v[162:163], 0, s[2:3]
	s_mov_b64 s[2:3], 0x20400
	v_lshl_add_u64 v[100:101], v[162:163], 0, s[2:3]
	s_waitcnt lgkmcnt(0)
	v_add_f32_e32 v82, v82, v83
	ds_bpermute_b32 v83, v119, v82
	v_cvt_pk_bf16_f32 v92, v92, v93
	v_cvt_pk_bf16_f32 v93, v104, v105
	global_store_dwordx4 v[98:99], v[90:93], off
	v_cvt_pk_bf16_f32 v84, v86, v87
	v_cvt_pk_bf16_f32 v85, v88, v89
	v_cvt_pk_bf16_f32 v86, v94, v95
	v_cvt_pk_bf16_f32 v87, v96, v97
	global_store_dwordx4 v[100:101], v[84:87], off
	s_and_saveexec_b64 s[2:3], s[4:5]
	s_cbranch_execz .LBB0_500
	s_waitcnt lgkmcnt(0)
	v_add_f32_e32 v82, v82, v83
	ds_write_b32 v172, v82 offset:512
; __device__ __forceinline__ u32x4 pack8(f32x4 v0, f32x4 v1) { u32x4 w; w.x = cvt_pk_bf16(v0[0], v0[1]); w.y = cvt_pk_bf16(v0[2], v0[3]); w.z = cvt_pk_bf16(v1[0], v1[1]); w.w = cvt_pk_bf16(v1[2], v1[3]); return w; }
;     __device__ __forceinline__ void operator()(const f32x4 (&acc)[2][2][4][2], const Unit& u, int wr, int wc, int fr, int fq) const {
;     ...
;             for (int ai = 0; ai < 2; ++ai) {
;                 u32x4 old[4][2];
; #pragma unroll
;                 for (int m = 0; m < 4; ++m)
; #pragma unroll
;                     for (int bj = 0; bj < 2; ++bj) old[m][bj] = *(const u32x4*)(xbb + ((size_t)(ai * 8 + m) * 64 + bj) * 512);
; #pragma unroll
;                 for (int m = 0; m < 4; ++m) { const int rl = ai * HALF + wr * 64 + m * 16 + fr; bf16_t* rowp = xbb + (size_t)(ai * 8 + m) * 64 * 512; float q = 0.f;
; #pragma unroll
;                     for (int bj = 0; bj < 2; ++bj) { const u32x4 o = old[m][bj];
;                         f32x4 x0 = (f32x4){__uint_as_float(o.x << 16), __uint_as_float(o.x & 0xffff0000u), __uint_as_float(o.y << 16), __uint_as_float(o.y & 0xffff0000u)} + acc[ai][bj][m][0];
;                         f32x4 x1 = (f32x4){__uint_as_float(o.z << 16), __uint_as_float(o.z & 0xffff0000u), __uint_as_float(o.w << 16), __uint_as_float(o.w & 0xffff0000u)} + acc[ai][bj][m][1];
;                         q += ((x0[0] * x0[0] + x0[1] * x0[1]) + (x0[2] * x0[2] + x0[3] * x0[3])) + ((x1[0] * x1[0] + x1[1] * x1[1]) + (x1[2] * x1[2] + x1[3] * x1[3]));
;                         *(u32x4*)(rowp + bj * 512) = pack8(x0, x1); }
;                     q += __shfl_xor(q, 16); q += __shfl_xor(q, 32);
;                     if (fq == 0) PL[rl * 4 + wc] = q; } }
.LBB0_500:
	s_or_b64 exec, exec, s[2:3]
	s_nop 0
	s_waitcnt vmcnt(15)
	v_lshlrev_b32_e32 v86, 16, v126
	v_and_b32_e32 v87, 0xffff0000, v126
	v_lshlrev_b32_e32 v88, 16, v127
	v_and_b32_e32 v89, 0xffff0000, v127
	v_pk_add_f32 v[80:81], v[80:81], v[88:89]
	v_pk_add_f32 v[78:79], v[78:79], v[86:87]
	v_lshlrev_b32_e32 v86, 16, v128
	v_and_b32_e32 v87, 0xffff0000, v128
	v_lshlrev_b32_e32 v88, 16, v129
	v_and_b32_e32 v89, 0xffff0000, v129
	v_pk_add_f32 v[88:89], v[76:77], v[88:89]
	v_pk_add_f32 v[76:77], v[74:75], v[86:87]
	v_mul_f32_e32 v74, v79, v79
	v_mul_f32_e32 v75, v81, v81
	v_fmac_f32_e32 v74, v78, v78
	v_fmac_f32_e32 v75, v80, v80
	v_add_f32_e32 v74, v74, v75
	v_mul_f32_e32 v75, v77, v77
	v_mul_f32_e32 v86, v89, v89
	v_fmac_f32_e32 v75, v76, v76
	v_fmac_f32_e32 v86, v88, v88
	v_add_f32_e32 v75, v75, v86
	v_add_f32_e32 v86, v74, v75
	v_cvt_pk_bf16_f32 v74, v78, v79
	v_cvt_pk_bf16_f32 v75, v80, v81
	s_nop 0
	s_waitcnt vmcnt(14)
	v_lshlrev_b32_e32 v78, 16, v114
	v_and_b32_e32 v79, 0xffff0000, v114
	v_lshlrev_b32_e32 v80, 16, v115
	v_and_b32_e32 v81, 0xffff0000, v115
	v_pk_add_f32 v[72:73], v[72:73], v[80:81]
	v_pk_add_f32 v[70:71], v[70:71], v[78:79]
	v_lshlrev_b32_e32 v78, 16, v116
	v_and_b32_e32 v79, 0xffff0000, v116
	v_lshlrev_b32_e32 v80, 16, v117
	v_and_b32_e32 v81, 0xffff0000, v117
	v_pk_add_f32 v[78:79], v[66:67], v[78:79]
	v_mul_f32_e32 v66, v71, v71
	v_mul_f32_e32 v67, v73, v73
	v_pk_add_f32 v[80:81], v[68:69], v[80:81]
	v_fmac_f32_e32 v66, v70, v70
	v_fmac_f32_e32 v67, v72, v72
	v_add_f32_e32 v66, v66, v67
	v_mul_f32_e32 v67, v79, v79
	v_mul_f32_e32 v68, v81, v81
	v_fmac_f32_e32 v67, v78, v78
	v_fmac_f32_e32 v68, v80, v80
	v_add_f32_e32 v67, v67, v68
	v_add_f32_e32 v66, v66, v67
	v_add_f32_e32 v66, v86, v66
	ds_bpermute_b32 v67, v118, v66
	s_mov_b64 s[2:3], 0x30000
	s_waitcnt lgkmcnt(1)
	v_lshl_add_u64 v[82:83], v[162:163], 0, s[2:3]
	s_mov_b64 s[2:3], 0x30400
	v_lshl_add_u64 v[84:85], v[162:163], 0, s[2:3]
	s_waitcnt lgkmcnt(0)
	v_add_f32_e32 v66, v66, v67
	ds_bpermute_b32 v67, v119, v66
	v_cvt_pk_bf16_f32 v76, v76, v77
	v_cvt_pk_bf16_f32 v77, v88, v89
	global_store_dwordx4 v[82:83], v[74:77], off
	v_cvt_pk_bf16_f32 v68, v70, v71
	v_cvt_pk_bf16_f32 v69, v72, v73
	v_cvt_pk_bf16_f32 v70, v78, v79
	v_cvt_pk_bf16_f32 v71, v80, v81
	global_store_dwordx4 v[84:85], v[68:71], off
	s_and_saveexec_b64 s[2:3], s[4:5]
	s_cbranch_execz .LBB0_502
	s_waitcnt lgkmcnt(0)
	v_add_f32_e32 v66, v66, v67
	ds_write_b32 v172, v66 offset:768
.LBB0_502:
	s_or_b64 exec, exec, s[2:3]
	v_add_co_u32_e32 v90, vcc, 0x80000, v162
	s_nop 1
	v_addc_co_u32_e32 v91, vcc, 0, v163, vcc
	s_nop 0
	s_nop 0
	v_add_co_u32_e32 v66, vcc, 0x90000, v162
	s_nop 0
	s_waitcnt vmcnt(15)
	v_lshlrev_b32_e32 v100, 16, v194
	s_waitcnt lgkmcnt(0)
	v_addc_co_u32_e32 v67, vcc, 0, v163, vcc
	s_nop 0
	s_nop 0
	v_add_co_u32_e32 v66, vcc, 0xa0000, v162
	v_and_b32_e32 v101, 0xffff0000, v194
	s_nop 0
	v_addc_co_u32_e32 v67, vcc, 0, v163, vcc
	s_nop 0
	s_nop 0
	v_add_co_u32_e32 v66, vcc, 0xb0000, v162
	v_lshlrev_b32_e32 v92, 16, v195
	s_nop 0
	v_addc_co_u32_e32 v67, vcc, 0, v163, vcc
	s_nop 0
	s_nop 0
	s_nop 0
	v_and_b32_e32 v93, 0xffff0000, v195
	v_pk_add_f32 v[64:65], v[64:65], v[92:93]
	v_pk_add_f32 v[62:63], v[62:63], v[100:101]
	v_lshlrev_b32_e32 v92, 16, v196
	v_and_b32_e32 v93, 0xffff0000, v196
	v_lshlrev_b32_e32 v94, 16, v197
	v_and_b32_e32 v95, 0xffff0000, v197
	v_pk_add_f32 v[94:95], v[60:61], v[94:95]
	v_pk_add_f32 v[60:61], v[58:59], v[92:93]
	v_mul_f32_e32 v58, v63, v63
	v_mul_f32_e32 v59, v65, v65
	v_fmac_f32_e32 v58, v62, v62
	v_fmac_f32_e32 v59, v64, v64
	v_add_f32_e32 v58, v58, v59
	v_mul_f32_e32 v59, v61, v61
	v_mul_f32_e32 v92, v95, v95
	v_fmac_f32_e32 v59, v60, v60
	v_fmac_f32_e32 v92, v94, v94
	v_add_f32_e32 v59, v59, v92
	v_add_f32_e32 v92, v58, v59
	v_cvt_pk_bf16_f32 v58, v62, v63
	v_cvt_pk_bf16_f32 v59, v64, v65
	v_cvt_pk_bf16_f32 v60, v60, v61
	v_cvt_pk_bf16_f32 v61, v94, v95
	global_store_dwordx4 v[90:91], v[58:61], off
	s_nop 0
	s_nop 0
	s_waitcnt vmcnt(15)
	v_lshlrev_b32_e32 v58, 16, v198
	v_and_b32_e32 v59, 0xffff0000, v198
	v_lshlrev_b32_e32 v60, 16, v199
	v_and_b32_e32 v61, 0xffff0000, v199
	v_pk_add_f32 v[56:57], v[56:57], v[60:61]
	v_pk_add_f32 v[54:55], v[54:55], v[58:59]
	v_lshlrev_b32_e32 v58, 16, v200
	v_and_b32_e32 v59, 0xffff0000, v200
	v_lshlrev_b32_e32 v60, 16, v201
	v_and_b32_e32 v61, 0xffff0000, v201
	v_pk_add_f32 v[60:61], v[52:53], v[60:61]
	v_pk_add_f32 v[52:53], v[50:51], v[58:59]
	v_mul_f32_e32 v50, v55, v55
	v_mul_f32_e32 v51, v57, v57
	v_fmac_f32_e32 v50, v54, v54
	v_fmac_f32_e32 v51, v56, v56
	v_add_f32_e32 v50, v50, v51
	v_mul_f32_e32 v51, v53, v53
	v_mul_f32_e32 v58, v61, v61
	v_fmac_f32_e32 v51, v52, v52
	v_fmac_f32_e32 v58, v60, v60
	v_add_f32_e32 v51, v51, v58
	v_add_f32_e32 v50, v50, v51
	v_add_f32_e32 v58, v92, v50
	v_cvt_pk_bf16_f32 v50, v54, v55
	v_cvt_pk_bf16_f32 v51, v56, v57
	v_cvt_pk_bf16_f32 v52, v52, v53
	v_cvt_pk_bf16_f32 v53, v60, v61
	global_store_dwordx4 v[90:91], v[50:53], off offset:1024
	ds_bpermute_b32 v50, v118, v58
	s_waitcnt lgkmcnt(0)
	v_add_f32_e32 v50, v58, v50
	ds_bpermute_b32 v51, v119, v50
	s_and_saveexec_b64 s[2:3], s[4:5]
	s_cbranch_execz .LBB0_504
	s_waitcnt lgkmcnt(0)
	v_add_f32_e32 v50, v50, v51
	ds_write_b32 v172, v50 offset:2048
; __device__ __forceinline__ u32x4 pack8(f32x4 v0, f32x4 v1) { u32x4 w; w.x = cvt_pk_bf16(v0[0], v0[1]); w.y = cvt_pk_bf16(v0[2], v0[3]); w.z = cvt_pk_bf16(v1[0], v1[1]); w.w = cvt_pk_bf16(v1[2], v1[3]); return w; }
;     __device__ __forceinline__ void operator()(const f32x4 (&acc)[2][2][4][2], const Unit& u, int wr, int wc, int fr, int fq) const {
;     ...
;                     for (int bj = 0; bj < 2; ++bj) { const u32x4 o = old[m][bj];
;                         f32x4 x0 = (f32x4){__uint_as_float(o.x << 16), __uint_as_float(o.x & 0xffff0000u), __uint_as_float(o.y << 16), __uint_as_float(o.y & 0xffff0000u)} + acc[ai][bj][m][0];
;                         f32x4 x1 = (f32x4){__uint_as_float(o.z << 16), __uint_as_float(o.z & 0xffff0000u), __uint_as_float(o.w << 16), __uint_as_float(o.w & 0xffff0000u)} + acc[ai][bj][m][1];
;                         q += ((x0[0] * x0[0] + x0[1] * x0[1]) + (x0[2] * x0[2] + x0[3] * x0[3])) + ((x1[0] * x1[0] + x1[1] * x1[1]) + (x1[2] * x1[2] + x1[3] * x1[3]));
;                         *(u32x4*)(rowp + bj * 512) = pack8(x0, x1); }
;                     q += __shfl_xor(q, 16); q += __shfl_xor(q, 32);
;                     if (fq == 0) PL[rl * 4 + wc] = q; } }
.LBB0_504:
	s_or_b64 exec, exec, s[2:3]
	s_nop 0
	s_waitcnt vmcnt(15)
	v_lshlrev_b32_e32 v54, 16, v202
	v_and_b32_e32 v55, 0xffff0000, v202
	v_lshlrev_b32_e32 v56, 16, v203
	v_and_b32_e32 v57, 0xffff0000, v203
	v_pk_add_f32 v[48:49], v[48:49], v[56:57]
	v_pk_add_f32 v[46:47], v[46:47], v[54:55]
	v_lshlrev_b32_e32 v54, 16, v204
	v_and_b32_e32 v55, 0xffff0000, v204
	v_lshlrev_b32_e32 v56, 16, v205
	v_and_b32_e32 v57, 0xffff0000, v205
	v_pk_add_f32 v[56:57], v[44:45], v[56:57]
	v_pk_add_f32 v[44:45], v[42:43], v[54:55]
	v_mul_f32_e32 v42, v47, v47
	v_mul_f32_e32 v43, v49, v49
	v_fmac_f32_e32 v42, v46, v46
	v_fmac_f32_e32 v43, v48, v48
	v_add_f32_e32 v42, v42, v43
	v_mul_f32_e32 v43, v45, v45
	v_mul_f32_e32 v54, v57, v57
	v_fmac_f32_e32 v43, v44, v44
	v_fmac_f32_e32 v54, v56, v56
	v_add_f32_e32 v43, v43, v54
	v_add_f32_e32 v54, v42, v43
	v_cvt_pk_bf16_f32 v42, v46, v47
	v_cvt_pk_bf16_f32 v43, v48, v49
	s_nop 0
	s_waitcnt vmcnt(14)
	v_lshlrev_b32_e32 v46, 16, v206
	v_and_b32_e32 v47, 0xffff0000, v206
	v_lshlrev_b32_e32 v48, 16, v207
	v_and_b32_e32 v49, 0xffff0000, v207
	v_pk_add_f32 v[40:41], v[40:41], v[48:49]
	v_pk_add_f32 v[38:39], v[38:39], v[46:47]
	v_lshlrev_b32_e32 v46, 16, v208
	v_and_b32_e32 v47, 0xffff0000, v208
	v_lshlrev_b32_e32 v48, 16, v209
	v_and_b32_e32 v49, 0xffff0000, v209
	v_pk_add_f32 v[46:47], v[34:35], v[46:47]
	v_mul_f32_e32 v34, v39, v39
	v_mul_f32_e32 v35, v41, v41
	v_pk_add_f32 v[48:49], v[36:37], v[48:49]
	v_fmac_f32_e32 v34, v38, v38
	v_fmac_f32_e32 v35, v40, v40
	v_add_f32_e32 v34, v34, v35
	v_mul_f32_e32 v35, v47, v47
	v_mul_f32_e32 v36, v49, v49
	v_fmac_f32_e32 v35, v46, v46
	v_fmac_f32_e32 v36, v48, v48
	v_add_f32_e32 v35, v35, v36
	v_add_f32_e32 v34, v34, v35
	v_add_f32_e32 v34, v54, v34
	ds_bpermute_b32 v35, v118, v34
	s_mov_b64 s[2:3], 0x90000
	s_waitcnt lgkmcnt(1)
	v_lshl_add_u64 v[50:51], v[162:163], 0, s[2:3]
	s_mov_b64 s[2:3], 0x90400
	v_lshl_add_u64 v[52:53], v[162:163], 0, s[2:3]
	s_waitcnt lgkmcnt(0)
	v_add_f32_e32 v34, v34, v35
	ds_bpermute_b32 v35, v119, v34
	v_cvt_pk_bf16_f32 v44, v44, v45
	v_cvt_pk_bf16_f32 v45, v56, v57
	global_store_dwordx4 v[50:51], v[42:45], off
	v_cvt_pk_bf16_f32 v36, v38, v39
	v_cvt_pk_bf16_f32 v37, v40, v41
	v_cvt_pk_bf16_f32 v38, v46, v47
	v_cvt_pk_bf16_f32 v39, v48, v49
	global_store_dwordx4 v[52:53], v[36:39], off
	s_and_saveexec_b64 s[2:3], s[4:5]
	s_cbranch_execz .LBB0_506
	s_waitcnt lgkmcnt(0)
	v_add_f32_e32 v34, v34, v35
	ds_write_b32 v172, v34 offset:2304
; __device__ __forceinline__ u32x4 pack8(f32x4 v0, f32x4 v1) { u32x4 w; w.x = cvt_pk_bf16(v0[0], v0[1]); w.y = cvt_pk_bf16(v0[2], v0[3]); w.z = cvt_pk_bf16(v1[0], v1[1]); w.w = cvt_pk_bf16(v1[2], v1[3]); return w; }
;     __device__ __forceinline__ void operator()(const f32x4 (&acc)[2][2][4][2], const Unit& u, int wr, int wc, int fr, int fq) const {
;     ...
;                 for (int m = 0; m < 4; ++m) { const int rl = ai * HALF + wr * 64 + m * 16 + fr; bf16_t* rowp = xbb + (size_t)(ai * 8 + m) * 64 * 512; float q = 0.f;
; #pragma unroll
;                     for (int bj = 0; bj < 2; ++bj) { const u32x4 o = old[m][bj];
;                         f32x4 x0 = (f32x4){__uint_as_float(o.x << 16), __uint_as_float(o.x & 0xffff0000u), __uint_as_float(o.y << 16), __uint_as_float(o.y & 0xffff0000u)} + acc[ai][bj][m][0];
;                         f32x4 x1 = (f32x4){__uint_as_float(o.z << 16), __uint_as_float(o.z & 0xffff0000u), __uint_as_float(o.w << 16), __uint_as_float(o.w & 0xffff0000u)} + acc[ai][bj][m][1];
;                         q += ((x0[0] * x0[0] + x0[1] * x0[1]) + (x0[2] * x0[2] + x0[3] * x0[3])) + ((x1[0] * x1[0] + x1[1] * x1[1]) + (x1[2] * x1[2] + x1[3] * x1[3]));
;                         *(u32x4*)(rowp + bj * 512) = pack8(x0, x1); }
;                     q += __shfl_xor(q, 16); q += __shfl_xor(q, 32);
;                     if (fq == 0) PL[rl * 4 + wc] = q; } }
.LBB0_506:
	s_or_b64 exec, exec, s[2:3]
	s_nop 0
	s_waitcnt vmcnt(15)
	v_lshlrev_b32_e32 v38, 16, v210
	v_and_b32_e32 v39, 0xffff0000, v210
	v_lshlrev_b32_e32 v40, 16, v211
	v_and_b32_e32 v41, 0xffff0000, v211
	v_pk_add_f32 v[32:33], v[32:33], v[40:41]
	v_pk_add_f32 v[30:31], v[30:31], v[38:39]
	v_lshlrev_b32_e32 v38, 16, v212
	v_and_b32_e32 v39, 0xffff0000, v212
	v_lshlrev_b32_e32 v40, 16, v213
	v_and_b32_e32 v41, 0xffff0000, v213
	v_pk_add_f32 v[40:41], v[28:29], v[40:41]
	v_pk_add_f32 v[28:29], v[26:27], v[38:39]
	v_mul_f32_e32 v26, v31, v31
	v_mul_f32_e32 v27, v33, v33
	v_fmac_f32_e32 v26, v30, v30
	v_fmac_f32_e32 v27, v32, v32
	v_add_f32_e32 v26, v26, v27
	v_mul_f32_e32 v27, v29, v29
	v_mul_f32_e32 v38, v41, v41
	v_fmac_f32_e32 v27, v28, v28
	v_fmac_f32_e32 v38, v40, v40
	v_add_f32_e32 v27, v27, v38
	v_add_f32_e32 v38, v26, v27
	v_cvt_pk_bf16_f32 v26, v30, v31
	v_cvt_pk_bf16_f32 v27, v32, v33
	s_nop 0
	s_waitcnt vmcnt(14)
	v_lshlrev_b32_e32 v30, 16, v214
	v_and_b32_e32 v31, 0xffff0000, v214
	v_lshlrev_b32_e32 v32, 16, v215
	v_and_b32_e32 v33, 0xffff0000, v215
	v_pk_add_f32 v[24:25], v[24:25], v[32:33]
	v_pk_add_f32 v[22:23], v[22:23], v[30:31]
	v_lshlrev_b32_e32 v30, 16, v216
	v_and_b32_e32 v31, 0xffff0000, v216
	v_lshlrev_b32_e32 v32, 16, v217
	v_and_b32_e32 v33, 0xffff0000, v217
	v_pk_add_f32 v[30:31], v[18:19], v[30:31]
	v_mul_f32_e32 v18, v23, v23
	v_mul_f32_e32 v19, v25, v25
	v_pk_add_f32 v[32:33], v[20:21], v[32:33]
	v_fmac_f32_e32 v18, v22, v22
	v_fmac_f32_e32 v19, v24, v24
	v_add_f32_e32 v18, v18, v19
	v_mul_f32_e32 v19, v31, v31
	v_mul_f32_e32 v20, v33, v33
	v_fmac_f32_e32 v19, v30, v30
	v_fmac_f32_e32 v20, v32, v32
	v_add_f32_e32 v19, v19, v20
	v_add_f32_e32 v18, v18, v19
	v_add_f32_e32 v18, v38, v18
	ds_bpermute_b32 v19, v118, v18
	s_mov_b64 s[2:3], 0xa0000
	s_waitcnt lgkmcnt(1)
	v_lshl_add_u64 v[34:35], v[162:163], 0, s[2:3]
	s_mov_b64 s[2:3], 0xa0400
	v_lshl_add_u64 v[36:37], v[162:163], 0, s[2:3]
	s_waitcnt lgkmcnt(0)
	v_add_f32_e32 v18, v18, v19
	ds_bpermute_b32 v19, v119, v18
	v_cvt_pk_bf16_f32 v28, v28, v29
	v_cvt_pk_bf16_f32 v29, v40, v41
	global_store_dwordx4 v[34:35], v[26:29], off
	v_cvt_pk_bf16_f32 v20, v22, v23
	v_cvt_pk_bf16_f32 v21, v24, v25
	v_cvt_pk_bf16_f32 v22, v30, v31
	v_cvt_pk_bf16_f32 v23, v32, v33
	global_store_dwordx4 v[36:37], v[20:23], off
	s_and_saveexec_b64 s[2:3], s[4:5]
	s_cbranch_execz .LBB0_508
	s_waitcnt lgkmcnt(0)
	v_add_f32_e32 v18, v18, v19
	ds_write_b32 v172, v18 offset:2560
.LBB0_508:
	s_or_b64 exec, exec, s[2:3]
	s_nop 0
	s_waitcnt vmcnt(15)
	v_lshlrev_b32_e32 v22, 16, v218
	v_and_b32_e32 v23, 0xffff0000, v218
	v_lshlrev_b32_e32 v24, 16, v219
	v_and_b32_e32 v25, 0xffff0000, v219
	v_pk_add_f32 v[16:17], v[16:17], v[24:25]
	v_pk_add_f32 v[14:15], v[14:15], v[22:23]
	v_lshlrev_b32_e32 v22, 16, v220
	v_and_b32_e32 v23, 0xffff0000, v220
	v_lshlrev_b32_e32 v24, 16, v221
	v_and_b32_e32 v25, 0xffff0000, v221
	v_pk_add_f32 v[24:25], v[12:13], v[24:25]
	v_pk_add_f32 v[12:13], v[10:11], v[22:23]
	v_mul_f32_e32 v10, v15, v15
	v_mul_f32_e32 v11, v17, v17
	v_fmac_f32_e32 v10, v14, v14
	v_fmac_f32_e32 v11, v16, v16
	v_add_f32_e32 v10, v10, v11
	v_mul_f32_e32 v11, v13, v13
	v_mul_f32_e32 v22, v25, v25
	v_fmac_f32_e32 v11, v12, v12
	v_fmac_f32_e32 v22, v24, v24
	v_add_f32_e32 v11, v11, v22
	v_add_f32_e32 v22, v10, v11
	v_cvt_pk_bf16_f32 v10, v14, v15
	v_cvt_pk_bf16_f32 v11, v16, v17
	s_nop 0
	s_waitcnt vmcnt(14)
	v_lshlrev_b32_e32 v14, 16, v222
	v_and_b32_e32 v15, 0xffff0000, v222
	v_lshlrev_b32_e32 v16, 16, v223
	v_and_b32_e32 v17, 0xffff0000, v223
	v_pk_add_f32 v[8:9], v[8:9], v[16:17]
	v_pk_add_f32 v[6:7], v[6:7], v[14:15]
	v_lshlrev_b32_e32 v14, 16, v224
	v_and_b32_e32 v15, 0xffff0000, v224
	v_lshlrev_b32_e32 v16, 16, v225
	v_and_b32_e32 v17, 0xffff0000, v225
	v_pk_add_f32 v[14:15], v[2:3], v[14:15]
	v_mul_f32_e32 v2, v7, v7
	v_mul_f32_e32 v3, v9, v9
	v_pk_add_f32 v[16:17], v[4:5], v[16:17]
	v_fmac_f32_e32 v2, v6, v6
	v_fmac_f32_e32 v3, v8, v8
	v_add_f32_e32 v2, v2, v3
	v_mul_f32_e32 v3, v15, v15
	v_mul_f32_e32 v4, v17, v17
	v_fmac_f32_e32 v3, v14, v14
	v_fmac_f32_e32 v4, v16, v16
	v_add_f32_e32 v3, v3, v4
	v_add_f32_e32 v2, v2, v3
	v_add_f32_e32 v2, v22, v2
	ds_bpermute_b32 v3, v118, v2
	s_mov_b64 s[2:3], 0xb0000
	s_waitcnt lgkmcnt(1)
	v_lshl_add_u64 v[18:19], v[162:163], 0, s[2:3]
	s_mov_b64 s[2:3], 0xb0400
	v_lshl_add_u64 v[20:21], v[162:163], 0, s[2:3]
	s_waitcnt lgkmcnt(0)
	v_add_f32_e32 v2, v2, v3
	ds_bpermute_b32 v3, v119, v2
	v_cvt_pk_bf16_f32 v12, v12, v13
	v_cvt_pk_bf16_f32 v13, v24, v25
	global_store_dwordx4 v[18:19], v[10:13], off
	v_cvt_pk_bf16_f32 v4, v6, v7
	v_cvt_pk_bf16_f32 v5, v8, v9
	v_cvt_pk_bf16_f32 v6, v14, v15
	v_cvt_pk_bf16_f32 v7, v16, v17
	global_store_dwordx4 v[20:21], v[4:7], off
	s_and_saveexec_b64 s[2:3], s[4:5]
	s_cbranch_execz .LBB0_510
	s_waitcnt lgkmcnt(0)
	v_add_f32_e32 v2, v2, v3
	ds_write_b32 v172, v2 offset:2816

; #define PG8_LAS __attribute__((address_space(3)))
; __device__ __forceinline__ u32x4 pack8(f32x4 v0, f32x4 v1) { u32x4 w; w.x = cvt_pk_bf16(v0[0], v0[1]); w.y = cvt_pk_bf16(v0[2], v0[3]); w.z = cvt_pk_bf16(v1[0], v1[1]); w.w = cvt_pk_bf16(v1[2], v1[3]); return w; }
;     __device__ __forceinline__ void operator()(const f32x4 (&acc)[2][2][4][2], const Unit& u, int wr, int wc, int fr, int fq) const {
;     ...
;             bf16_t* xbb = XB + ((size_t)(u.pm * 16 + wr * 4) * 64 + u.pn * 8 + 2 * wc) * 512 + fr * 32 + (((fq * 16) ^ ((fr >> 3) << 5)) >> 1);
;             PG8_LAS float* PL = (PG8_LAS float*)xl;
; #pragma unroll
;             for (int ai = 0; ai < 2; ++ai) {
;                 u32x4 old[4][2];
; #pragma unroll
;                 for (int m = 0; m < 4; ++m)
; #pragma unroll
;                     for (int bj = 0; bj < 2; ++bj) old[m][bj] = *(const u32x4*)(xbb + ((size_t)(ai * 8 + m) * 64 + bj) * 512);
; #pragma unroll
;                 for (int m = 0; m < 4; ++m) { const int rl = ai * HALF + wr * 64 + m * 16 + fr; bf16_t* rowp = xbb + (size_t)(ai * 8 + m) * 64 * 512; float q = 0.f;
; #pragma unroll
;                     for (int bj = 0; bj < 2; ++bj) { const u32x4 o = old[m][bj];
;                         f32x4 x0 = (f32x4){__uint_as_float(o.x << 16), __uint_as_float(o.x & 0xffff0000u), __uint_as_float(o.y << 16), __uint_as_float(o.y & 0xffff0000u)} + acc[ai][bj][m][0];
;                         f32x4 x1 = (f32x4){__uint_as_float(o.z << 16), __uint_as_float(o.z & 0xffff0000u), __uint_as_float(o.w << 16), __uint_as_float(o.w & 0xffff0000u)} + acc[ai][bj][m][1];
;                         q += ((x0[0] * x0[0] + x0[1] * x0[1]) + (x0[2] * x0[2] + x0[3] * x0[3])) + ((x1[0] * x1[0] + x1[1] * x1[1]) + (x1[2] * x1[2] + x1[3] * x1[3]));
;                         *(u32x4*)(rowp + bj * 512) = pack8(x0, x1); }
;                     q += __shfl_xor(q, 16); q += __shfl_xor(q, 32);
;                     if (fq == 0) PL[rl * 4 + wc] = q; } }
.LBB0_1540:
	s_lshl_b32 s2, s2, 4
	s_add_i32 s2, s2, s67
	s_ashr_i32 s3, s2, 31
	s_lshl_b32 s37, s10, 3
	s_lshl_b64 s[2:3], s[2:3], 6
	s_ashr_i32 s39, s37, 31
	s_add_u32 s2, s2, s37
	s_addc_u32 s3, s3, s39
	s_or_b64 s[2:3], s[2:3], s[20:21]
	s_lshl_b64 s[2:3], s[2:3], 10
	v_lshl_add_u64 v[162:163], v[156:157], 0, s[2:3]
	global_load_dwordx4 v[174:177], v[162:163], off
	global_load_dwordx4 v[178:181], v[162:163], off offset:1024
	s_mov_b32 s2, 0x10000
	v_add_co_u32_e32 v114, vcc, s2, v162
	s_mov_b32 s2, 0x30000
	s_nop 0
	v_addc_co_u32_e32 v115, vcc, 0, v163, vcc
	global_load_dwordx4 v[150:153], v[114:115], off
	global_load_dwordx4 v[146:149], v[114:115], off offset:1024
	v_add_co_u32_e32 v114, vcc, s76, v162
	s_nop 0
	s_nop 0
	v_addc_co_u32_e32 v115, vcc, 0, v163, vcc
	global_load_dwordx4 v[142:145], v[114:115], off
	global_load_dwordx4 v[130:133], v[114:115], off offset:1024
	v_add_co_u32_e32 v114, vcc, s2, v162
	s_nop 0
	s_nop 0
	v_addc_co_u32_e32 v115, vcc, 0, v163, vcc
	global_load_dwordx4 v[126:129], v[114:115], off
	s_nop 0
	global_load_dwordx4 v[114:117], v[114:115], off offset:1024
	v_add_co_u32_e32 v226, vcc, 0x80000, v162
	s_nop 1
	v_addc_co_u32_e32 v227, vcc, 0, v163, vcc
	global_load_dwordx4 v[194:197], v[226:227], off
	global_load_dwordx4 v[198:201], v[226:227], off offset:1024
	v_add_co_u32_e32 v226, vcc, 0x90000, v162
	s_nop 1
	v_addc_co_u32_e32 v227, vcc, 0, v163, vcc
	global_load_dwordx4 v[202:205], v[226:227], off
	global_load_dwordx4 v[206:209], v[226:227], off offset:1024
	v_add_co_u32_e32 v226, vcc, 0xa0000, v162
	s_nop 1
	v_addc_co_u32_e32 v227, vcc, 0, v163, vcc
	global_load_dwordx4 v[210:213], v[226:227], off
	global_load_dwordx4 v[214:217], v[226:227], off offset:1024
	v_add_co_u32_e32 v226, vcc, 0xb0000, v162
	s_nop 1
	v_addc_co_u32_e32 v227, vcc, 0, v163, vcc
	global_load_dwordx4 v[218:221], v[226:227], off
	global_load_dwordx4 v[222:225], v[226:227], off offset:1024
	s_waitcnt vmcnt(15)
	v_lshlrev_b32_e32 v184, 16, v174
	v_and_b32_e32 v185, 0xffff0000, v174
	v_lshlrev_b32_e32 v174, 16, v175
	v_and_b32_e32 v175, 0xffff0000, v175
	v_pk_add_f32 v[140:141], v[140:141], v[174:175]
	v_pk_add_f32 v[138:139], v[138:139], v[184:185]
	v_lshlrev_b32_e32 v174, 16, v176
	v_and_b32_e32 v175, 0xffff0000, v176
	v_lshlrev_b32_e32 v176, 16, v177
	v_and_b32_e32 v177, 0xffff0000, v177
	v_pk_add_f32 v[176:177], v[136:137], v[176:177]
	v_pk_add_f32 v[136:137], v[134:135], v[174:175]
	v_mul_f32_e32 v134, v139, v139
	v_mul_f32_e32 v135, v141, v141
	v_fmac_f32_e32 v134, v138, v138
	v_fmac_f32_e32 v135, v140, v140
	v_add_f32_e32 v134, v134, v135
	v_mul_f32_e32 v135, v137, v137
	v_mul_f32_e32 v173, v177, v177
	v_fmac_f32_e32 v135, v136, v136
	v_fmac_f32_e32 v173, v176, v176
	v_add_f32_e32 v135, v135, v173
	v_add_f32_e32 v173, v134, v135
	v_cvt_pk_bf16_f32 v134, v138, v139
	v_cvt_pk_bf16_f32 v135, v140, v141
	v_cvt_pk_bf16_f32 v136, v136, v137
	v_cvt_pk_bf16_f32 v137, v176, v177
	global_store_dwordx4 v[162:163], v[134:137], off
	s_nop 1
	s_waitcnt vmcnt(15)
	v_lshlrev_b32_e32 v134, 16, v178
	v_and_b32_e32 v135, 0xffff0000, v178
	v_lshlrev_b32_e32 v136, 16, v179
	v_and_b32_e32 v137, 0xffff0000, v179
	v_pk_add_f32 v[124:125], v[124:125], v[136:137]
	v_pk_add_f32 v[122:123], v[122:123], v[134:135]
	v_lshlrev_b32_e32 v134, 16, v180
	v_and_b32_e32 v135, 0xffff0000, v180
	v_lshlrev_b32_e32 v136, 16, v181
	v_and_b32_e32 v137, 0xffff0000, v181
	v_pk_add_f32 v[136:137], v[120:121], v[136:137]
	v_pk_add_f32 v[120:121], v[118:119], v[134:135]
	v_mul_f32_e32 v118, v123, v123
	v_mul_f32_e32 v119, v125, v125
	v_fmac_f32_e32 v118, v122, v122
	v_fmac_f32_e32 v119, v124, v124
	v_add_f32_e32 v118, v118, v119
	v_mul_f32_e32 v119, v121, v121
	v_mul_f32_e32 v134, v137, v137
	v_fmac_f32_e32 v119, v120, v120
	v_fmac_f32_e32 v134, v136, v136
	v_add_f32_e32 v119, v119, v134
	v_add_f32_e32 v118, v118, v119
	v_add_f32_e32 v134, v173, v118
	v_cvt_pk_bf16_f32 v118, v122, v123
	v_cvt_pk_bf16_f32 v119, v124, v125
	v_cvt_pk_bf16_f32 v120, v120, v121
	v_cvt_pk_bf16_f32 v121, v136, v137
	global_store_dwordx4 v[162:163], v[118:121], off offset:1024
	s_nop 1
	v_and_b32_e32 v119, 64, v171
	v_xor_b32_e32 v118, 16, v171
	v_add_u32_e32 v119, 64, v119
	v_cmp_lt_i32_e32 vcc, v118, v119
	v_xor_b32_e32 v121, 32, v171
	s_nop 0
	v_cndmask_b32_e32 v118, v171, v118, vcc
	v_lshlrev_b32_e32 v118, 2, v118
	ds_bpermute_b32 v120, v118, v134
	v_cmp_lt_i32_e32 vcc, v121, v119
	s_waitcnt lgkmcnt(0)
	v_add_f32_e32 v120, v134, v120
	v_cndmask_b32_e32 v119, v171, v121, vcc
	v_lshlrev_b32_e32 v119, 2, v119
	ds_bpermute_b32 v121, v119, v120
	s_and_saveexec_b64 s[2:3], s[4:5]
	s_cbranch_execz .LBB0_1542
	s_waitcnt lgkmcnt(0)
	v_add_f32_e32 v120, v120, v121
	ds_write_b32 v172, v120

; #define PG8_LAS __attribute__((address_space(3)))
; __device__ __forceinline__ u32x4 pack8(f32x4 v0, f32x4 v1) { u32x4 w; w.x = cvt_pk_bf16(v0[0], v0[1]); w.y = cvt_pk_bf16(v0[2], v0[3]); w.z = cvt_pk_bf16(v1[0], v1[1]); w.w = cvt_pk_bf16(v1[2], v1[3]); return w; }
;     __device__ __forceinline__ void operator()(const f32x4 (&acc)[2][2][4][2], const Unit& u, int wr, int wc, int fr, int fq) const {
;     ...
;             bf16_t* xbb = XB + ((size_t)(u.pm * 16 + wr * 4) * 64 + u.pn * 8 + 2 * wc) * 512 + fr * 32 + (((fq * 16) ^ ((fr >> 3) << 5)) >> 1);
;             PG8_LAS float* PL = (PG8_LAS float*)xl;
; #pragma unroll
;             for (int ai = 0; ai < 2; ++ai) {
;                 u32x4 old[4][2];
; #pragma unroll
;                 for (int m = 0; m < 4; ++m)
; #pragma unroll
;                     for (int bj = 0; bj < 2; ++bj) old[m][bj] = *(const u32x4*)(xbb + ((size_t)(ai * 8 + m) * 64 + bj) * 512);
; #pragma unroll
;                 for (int m = 0; m < 4; ++m) { const int rl = ai * HALF + wr * 64 + m * 16 + fr; bf16_t* rowp = xbb + (size_t)(ai * 8 + m) * 64 * 512; float q = 0.f;
; #pragma unroll
;                     for (int bj = 0; bj < 2; ++bj) { const u32x4 o = old[m][bj];
;                         f32x4 x0 = (f32x4){__uint_as_float(o.x << 16), __uint_as_float(o.x & 0xffff0000u), __uint_as_float(o.y << 16), __uint_as_float(o.y & 0xffff0000u)} + acc[ai][bj][m][0];
;                         f32x4 x1 = (f32x4){__uint_as_float(o.z << 16), __uint_as_float(o.z & 0xffff0000u), __uint_as_float(o.w << 16), __uint_as_float(o.w & 0xffff0000u)} + acc[ai][bj][m][1];
;                         q += ((x0[0] * x0[0] + x0[1] * x0[1]) + (x0[2] * x0[2] + x0[3] * x0[3])) + ((x1[0] * x1[0] + x1[1] * x1[1]) + (x1[2] * x1[2] + x1[3] * x1[3]));
;                         *(u32x4*)(rowp + bj * 512) = pack8(x0, x1); }
;                     q += __shfl_xor(q, 16); q += __shfl_xor(q, 32);
;                     if (fq == 0) PL[rl * 4 + wc] = q; } }
.LBB0_2004:
	s_lshl_b32 s2, s2, 4
	s_add_i32 s2, s2, s67
	s_ashr_i32 s3, s2, 31
	s_lshl_b32 s39, s10, 3
	s_lshl_b64 s[2:3], s[2:3], 6
	s_ashr_i32 s41, s39, 31
	s_add_u32 s2, s2, s39
	s_addc_u32 s3, s3, s41
	s_or_b64 s[2:3], s[2:3], s[20:21]
	s_lshl_b64 s[2:3], s[2:3], 10
	v_lshl_add_u64 v[170:171], v[164:165], 0, s[2:3]
	global_load_dwordx4 v[158:161], v[170:171], off
	global_load_dwordx4 v[154:157], v[170:171], off offset:1024
	s_mov_b32 s2, 0x10000
	v_add_co_u32_e32 v130, vcc, s2, v170
	s_mov_b32 s3, 0x30000
	s_nop 0
	v_addc_co_u32_e32 v131, vcc, 0, v171, vcc
	v_add_co_u32_e32 v132, vcc, s72, v170
	global_load_dwordx4 v[150:153], v[130:131], off
	global_load_dwordx4 v[146:149], v[130:131], off offset:1024
	v_addc_co_u32_e32 v133, vcc, 0, v171, vcc
	v_add_co_u32_e32 v130, vcc, s3, v170
	global_load_dwordx4 v[142:145], v[132:133], off
	global_load_dwordx4 v[138:141], v[132:133], off offset:1024
	v_addc_co_u32_e32 v131, vcc, 0, v171, vcc
	global_load_dwordx4 v[134:137], v[130:131], off
	s_nop 0
	global_load_dwordx4 v[130:133], v[130:131], off offset:1024
	v_add_co_u32_e32 v226, vcc, 0x80000, v170
	s_nop 1
	v_addc_co_u32_e32 v227, vcc, 0, v171, vcc
	global_load_dwordx4 v[194:197], v[226:227], off
	global_load_dwordx4 v[198:201], v[226:227], off offset:1024
	v_add_co_u32_e32 v226, vcc, 0x90000, v170
	s_nop 1
	v_addc_co_u32_e32 v227, vcc, 0, v171, vcc
	global_load_dwordx4 v[202:205], v[226:227], off
	global_load_dwordx4 v[206:209], v[226:227], off offset:1024
	v_add_co_u32_e32 v226, vcc, 0xa0000, v170
	s_nop 1
	v_addc_co_u32_e32 v227, vcc, 0, v171, vcc
	global_load_dwordx4 v[210:213], v[226:227], off
	global_load_dwordx4 v[214:217], v[226:227], off offset:1024
	v_add_co_u32_e32 v226, vcc, 0xb0000, v170
	s_nop 1
	v_addc_co_u32_e32 v227, vcc, 0, v171, vcc
	global_load_dwordx4 v[218:221], v[226:227], off
	global_load_dwordx4 v[222:225], v[226:227], off offset:1024
	v_and_b32_e32 v184, 64, v179
	v_xor_b32_e32 v181, 16, v179
	v_add_u32_e32 v184, 64, v184
	v_xor_b32_e32 v185, 32, v179
	v_cmp_lt_i32_e32 vcc, v181, v184
	s_nop 0
	s_waitcnt vmcnt(15)
	v_lshlrev_b32_e32 v186, 16, v160
	v_cndmask_b32_e32 v181, v179, v181, vcc
	v_cmp_lt_i32_e32 vcc, v185, v184
	v_lshlrev_b32_e32 v184, 16, v158
	v_and_b32_e32 v187, 0xffff0000, v160
	v_cndmask_b32_e32 v192, v179, v185, vcc
	v_and_b32_e32 v185, 0xffff0000, v158
	v_lshlrev_b32_e32 v158, 16, v159
	v_and_b32_e32 v159, 0xffff0000, v159
	v_lshlrev_b32_e32 v160, 16, v161
	v_and_b32_e32 v161, 0xffff0000, v161
	s_waitcnt vmcnt(14)
	v_lshlrev_b32_e32 v188, 16, v154
	v_and_b32_e32 v189, 0xffff0000, v154
	v_lshlrev_b32_e32 v154, 16, v155
	v_and_b32_e32 v155, 0xffff0000, v155
	v_lshlrev_b32_e32 v190, 16, v156
	v_and_b32_e32 v191, 0xffff0000, v156
	v_lshlrev_b32_e32 v156, 16, v157
	v_and_b32_e32 v157, 0xffff0000, v157
	v_pk_add_f32 v[128:129], v[128:129], v[158:159]
	v_pk_add_f32 v[126:127], v[126:127], v[184:185]
	v_pk_add_f32 v[124:125], v[124:125], v[160:161]
	v_pk_add_f32 v[122:123], v[122:123], v[186:187]
	v_pk_add_f32 v[120:121], v[120:121], v[154:155]
	v_pk_add_f32 v[118:119], v[118:119], v[188:189]
	v_pk_add_f32 v[154:155], v[116:117], v[156:157]
	v_pk_add_f32 v[156:157], v[114:115], v[190:191]
	v_mul_f32_e32 v116, v127, v127
	v_mul_f32_e32 v117, v129, v129
	v_mul_f32_e32 v158, v123, v123
	v_mul_f32_e32 v159, v125, v125
	v_cvt_pk_bf16_f32 v114, v126, v127
	v_cvt_pk_bf16_f32 v115, v128, v129
	v_mul_f32_e32 v127, v119, v119
	v_mul_f32_e32 v129, v121, v121
	v_mul_f32_e32 v160, v157, v157
	v_mul_f32_e32 v161, v155, v155
	v_fmac_f32_e32 v116, v126, v126
	v_fmac_f32_e32 v117, v128, v128
	v_fmac_f32_e32 v158, v122, v122
	v_fmac_f32_e32 v159, v124, v124
	v_fmac_f32_e32 v127, v118, v118
	v_fmac_f32_e32 v129, v120, v120
	v_fmac_f32_e32 v160, v156, v156
	v_fmac_f32_e32 v161, v154, v154
	v_add_f32_e32 v116, v116, v117
	v_add_f32_e32 v117, v158, v159
	v_add_f32_e32 v126, v127, v129
	v_add_f32_e32 v127, v160, v161
	v_add_f32_e32 v116, v116, v117
	v_add_f32_e32 v117, v126, v127
	v_lshlrev_b32_e32 v181, 2, v181
	v_add_f32_e32 v126, v116, v117
	ds_bpermute_b32 v127, v181, v126
	v_cvt_pk_bf16_f32 v116, v122, v123
	v_cvt_pk_bf16_f32 v117, v124, v125
	global_store_dwordx4 v[170:171], v[114:117], off
	v_cvt_pk_bf16_f32 v118, v118, v119
	v_cvt_pk_bf16_f32 v119, v120, v121
	v_cvt_pk_bf16_f32 v120, v156, v157
	v_cvt_pk_bf16_f32 v121, v154, v155
	global_store_dwordx4 v[170:171], v[118:121], off offset:1024
	s_waitcnt lgkmcnt(0)
	v_add_f32_e32 v115, v126, v127
	v_lshlrev_b32_e32 v114, 2, v192
	ds_bpermute_b32 v116, v114, v115
	s_and_saveexec_b64 s[2:3], s[4:5]
	s_cbranch_execz .LBB0_2006
	s_waitcnt lgkmcnt(0)
	v_add_f32_e32 v115, v115, v116
	ds_write_b32 v180, v115
; __device__ __forceinline__ u32x4 pack8(f32x4 v0, f32x4 v1) { u32x4 w; w.x = cvt_pk_bf16(v0[0], v0[1]); w.y = cvt_pk_bf16(v0[2], v0[3]); w.z = cvt_pk_bf16(v1[0], v1[1]); w.w = cvt_pk_bf16(v1[2], v1[3]); return w; }
;     __device__ __forceinline__ void operator()(const f32x4 (&acc)[2][2][4][2], const Unit& u, int wr, int wc, int fr, int fq) const {
;     ...
;                 for (int m = 0; m < 4; ++m) { const int rl = ai * HALF + wr * 64 + m * 16 + fr; bf16_t* rowp = xbb + (size_t)(ai * 8 + m) * 64 * 512; float q = 0.f;
; #pragma unroll
;                     for (int bj = 0; bj < 2; ++bj) { const u32x4 o = old[m][bj];
;                         f32x4 x0 = (f32x4){__uint_as_float(o.x << 16), __uint_as_float(o.x & 0xffff0000u), __uint_as_float(o.y << 16), __uint_as_float(o.y & 0xffff0000u)} + acc[ai][bj][m][0];
;                         f32x4 x1 = (f32x4){__uint_as_float(o.z << 16), __uint_as_float(o.z & 0xffff0000u), __uint_as_float(o.w << 16), __uint_as_float(o.w & 0xffff0000u)} + acc[ai][bj][m][1];
;                         q += ((x0[0] * x0[0] + x0[1] * x0[1]) + (x0[2] * x0[2] + x0[3] * x0[3])) + ((x1[0] * x1[0] + x1[1] * x1[1]) + (x1[2] * x1[2] + x1[3] * x1[3]));
;                         *(u32x4*)(rowp + bj * 512) = pack8(x0, x1); }
;                     q += __shfl_xor(q, 16); q += __shfl_xor(q, 32);
;                     if (fq == 0) PL[rl * 4 + wc] = q; } }
.LBB0_2006:
	s_or_b64 exec, exec, s[2:3]
	s_waitcnt vmcnt(15)
	v_lshlrev_b32_e32 v120, 16, v150
	v_and_b32_e32 v121, 0xffff0000, v150
	v_lshlrev_b32_e32 v122, 16, v151
	v_and_b32_e32 v123, 0xffff0000, v151
	v_pk_add_f32 v[112:113], v[112:113], v[122:123]
	v_pk_add_f32 v[110:111], v[110:111], v[120:121]
	v_lshlrev_b32_e32 v120, 16, v152
	v_and_b32_e32 v121, 0xffff0000, v152
	v_lshlrev_b32_e32 v122, 16, v153
	v_and_b32_e32 v123, 0xffff0000, v153
	v_pk_add_f32 v[122:123], v[108:109], v[122:123]
	v_pk_add_f32 v[108:109], v[106:107], v[120:121]
	v_mul_f32_e32 v106, v111, v111
	v_mul_f32_e32 v107, v113, v113
	v_fmac_f32_e32 v106, v110, v110
	v_fmac_f32_e32 v107, v112, v112
	v_add_f32_e32 v106, v106, v107
	v_mul_f32_e32 v107, v109, v109
	v_mul_f32_e32 v115, v123, v123
	v_fmac_f32_e32 v107, v108, v108
	v_fmac_f32_e32 v115, v122, v122
	v_add_f32_e32 v107, v107, v115
	v_add_f32_e32 v115, v106, v107
	v_cvt_pk_bf16_f32 v106, v110, v111
	v_cvt_pk_bf16_f32 v107, v112, v113
	s_waitcnt vmcnt(14)
	v_lshlrev_b32_e32 v110, 16, v146
	v_and_b32_e32 v111, 0xffff0000, v146
	v_lshlrev_b32_e32 v112, 16, v147
	v_and_b32_e32 v113, 0xffff0000, v147
	v_pk_add_f32 v[104:105], v[104:105], v[112:113]
	v_pk_add_f32 v[102:103], v[102:103], v[110:111]
	v_lshlrev_b32_e32 v110, 16, v148
	v_and_b32_e32 v111, 0xffff0000, v148
	v_lshlrev_b32_e32 v112, 16, v149
	v_and_b32_e32 v113, 0xffff0000, v149
	v_pk_add_f32 v[110:111], v[98:99], v[110:111]
	v_mul_f32_e32 v98, v103, v103
	v_mul_f32_e32 v99, v105, v105
	v_pk_add_f32 v[112:113], v[100:101], v[112:113]
	v_fmac_f32_e32 v98, v102, v102
	v_fmac_f32_e32 v99, v104, v104
	v_add_f32_e32 v98, v98, v99
	v_mul_f32_e32 v99, v111, v111
	v_mul_f32_e32 v100, v113, v113
	v_fmac_f32_e32 v99, v110, v110
	v_fmac_f32_e32 v100, v112, v112
	v_add_f32_e32 v99, v99, v100
	v_add_f32_e32 v98, v98, v99
	v_add_f32_e32 v98, v115, v98
	ds_bpermute_b32 v99, v181, v98
	s_mov_b64 s[2:3], 0x10000
	s_waitcnt lgkmcnt(1)
	v_lshl_add_u64 v[116:117], v[170:171], 0, s[2:3]
	s_mov_b64 s[2:3], 0x10400
	v_lshl_add_u64 v[118:119], v[170:171], 0, s[2:3]
	s_waitcnt lgkmcnt(0)
	v_add_f32_e32 v98, v98, v99
	ds_bpermute_b32 v99, v114, v98
	v_cvt_pk_bf16_f32 v108, v108, v109
	v_cvt_pk_bf16_f32 v109, v122, v123
	global_store_dwordx4 v[116:117], v[106:109], off
	v_cvt_pk_bf16_f32 v100, v102, v103
	v_cvt_pk_bf16_f32 v101, v104, v105
	v_cvt_pk_bf16_f32 v102, v110, v111
	v_cvt_pk_bf16_f32 v103, v112, v113
	global_store_dwordx4 v[118:119], v[100:103], off
	s_and_saveexec_b64 s[2:3], s[4:5]
	s_cbranch_execz .LBB0_2008
	s_waitcnt lgkmcnt(0)
	v_add_f32_e32 v98, v98, v99
	ds_write_b32 v180, v98 offset:256
.LBB0_2008:
	s_or_b64 exec, exec, s[2:3]
	s_waitcnt vmcnt(15)
	v_lshlrev_b32_e32 v102, 16, v142
	v_and_b32_e32 v103, 0xffff0000, v142
	v_lshlrev_b32_e32 v104, 16, v143
	v_and_b32_e32 v105, 0xffff0000, v143
	v_pk_add_f32 v[96:97], v[96:97], v[104:105]
	v_pk_add_f32 v[94:95], v[94:95], v[102:103]
	v_lshlrev_b32_e32 v102, 16, v144
	v_and_b32_e32 v103, 0xffff0000, v144
	v_lshlrev_b32_e32 v104, 16, v145
	v_and_b32_e32 v105, 0xffff0000, v145
	v_pk_add_f32 v[104:105], v[92:93], v[104:105]
	v_pk_add_f32 v[92:93], v[90:91], v[102:103]
	v_mul_f32_e32 v90, v95, v95
	v_mul_f32_e32 v91, v97, v97
	v_fmac_f32_e32 v90, v94, v94
	v_fmac_f32_e32 v91, v96, v96
	v_add_f32_e32 v90, v90, v91
	v_mul_f32_e32 v91, v93, v93
	v_mul_f32_e32 v102, v105, v105
	v_fmac_f32_e32 v91, v92, v92
	v_fmac_f32_e32 v102, v104, v104
	v_add_f32_e32 v91, v91, v102
	v_add_f32_e32 v102, v90, v91
	v_cvt_pk_bf16_f32 v90, v94, v95
	v_cvt_pk_bf16_f32 v91, v96, v97
	s_waitcnt vmcnt(14)
	v_lshlrev_b32_e32 v94, 16, v138
	v_and_b32_e32 v95, 0xffff0000, v138
	v_lshlrev_b32_e32 v96, 16, v139
	v_and_b32_e32 v97, 0xffff0000, v139
	v_pk_add_f32 v[88:89], v[88:89], v[96:97]
	v_pk_add_f32 v[86:87], v[86:87], v[94:95]
	v_lshlrev_b32_e32 v94, 16, v140
	v_and_b32_e32 v95, 0xffff0000, v140
	v_lshlrev_b32_e32 v96, 16, v141
	v_and_b32_e32 v97, 0xffff0000, v141
	v_pk_add_f32 v[94:95], v[82:83], v[94:95]
	v_mul_f32_e32 v82, v87, v87
	v_mul_f32_e32 v83, v89, v89
	v_pk_add_f32 v[96:97], v[84:85], v[96:97]
	v_fmac_f32_e32 v82, v86, v86
	v_fmac_f32_e32 v83, v88, v88
	v_add_f32_e32 v82, v82, v83
	v_mul_f32_e32 v83, v95, v95
	v_mul_f32_e32 v84, v97, v97
	v_fmac_f32_e32 v83, v94, v94
	v_fmac_f32_e32 v84, v96, v96
	v_add_f32_e32 v83, v83, v84
	v_add_f32_e32 v82, v82, v83
	v_add_f32_e32 v82, v102, v82
	ds_bpermute_b32 v83, v181, v82
	s_mov_b64 s[2:3], 0x20000
	s_waitcnt lgkmcnt(1)
	v_lshl_add_u64 v[98:99], v[170:171], 0, s[2:3]
	s_mov_b64 s[2:3], 0x20400
	v_lshl_add_u64 v[100:101], v[170:171], 0, s[2:3]
	s_waitcnt lgkmcnt(0)
	v_add_f32_e32 v82, v82, v83
	ds_bpermute_b32 v83, v114, v82
	v_cvt_pk_bf16_f32 v92, v92, v93
	v_cvt_pk_bf16_f32 v93, v104, v105
	global_store_dwordx4 v[98:99], v[90:93], off
	v_cvt_pk_bf16_f32 v84, v86, v87
	v_cvt_pk_bf16_f32 v85, v88, v89
	v_cvt_pk_bf16_f32 v86, v94, v95
	v_cvt_pk_bf16_f32 v87, v96, v97
	global_store_dwordx4 v[100:101], v[84:87], off
	s_and_saveexec_b64 s[2:3], s[4:5]
	s_cbranch_execz .LBB0_2010
	s_waitcnt lgkmcnt(0)
	v_add_f32_e32 v82, v82, v83
	ds_write_b32 v180, v82 offset:512
; __device__ __forceinline__ u32x4 pack8(f32x4 v0, f32x4 v1) { u32x4 w; w.x = cvt_pk_bf16(v0[0], v0[1]); w.y = cvt_pk_bf16(v0[2], v0[3]); w.z = cvt_pk_bf16(v1[0], v1[1]); w.w = cvt_pk_bf16(v1[2], v1[3]); return w; }
;     __device__ __forceinline__ void operator()(const f32x4 (&acc)[2][2][4][2], const Unit& u, int wr, int wc, int fr, int fq) const {
;     ...
;             for (int ai = 0; ai < 2; ++ai) {
;                 u32x4 old[4][2];
; #pragma unroll
;                 for (int m = 0; m < 4; ++m)
; #pragma unroll
;                     for (int bj = 0; bj < 2; ++bj) old[m][bj] = *(const u32x4*)(xbb + ((size_t)(ai * 8 + m) * 64 + bj) * 512);
; #pragma unroll
;                 for (int m = 0; m < 4; ++m) { const int rl = ai * HALF + wr * 64 + m * 16 + fr; bf16_t* rowp = xbb + (size_t)(ai * 8 + m) * 64 * 512; float q = 0.f;
; #pragma unroll
;                     for (int bj = 0; bj < 2; ++bj) { const u32x4 o = old[m][bj];
;                         f32x4 x0 = (f32x4){__uint_as_float(o.x << 16), __uint_as_float(o.x & 0xffff0000u), __uint_as_float(o.y << 16), __uint_as_float(o.y & 0xffff0000u)} + acc[ai][bj][m][0];
;                         f32x4 x1 = (f32x4){__uint_as_float(o.z << 16), __uint_as_float(o.z & 0xffff0000u), __uint_as_float(o.w << 16), __uint_as_float(o.w & 0xffff0000u)} + acc[ai][bj][m][1];
;                         q += ((x0[0] * x0[0] + x0[1] * x0[1]) + (x0[2] * x0[2] + x0[3] * x0[3])) + ((x1[0] * x1[0] + x1[1] * x1[1]) + (x1[2] * x1[2] + x1[3] * x1[3]));
;                         *(u32x4*)(rowp + bj * 512) = pack8(x0, x1); }
;                     q += __shfl_xor(q, 16); q += __shfl_xor(q, 32);
;                     if (fq == 0) PL[rl * 4 + wc] = q; } }
.LBB0_2010:
	s_or_b64 exec, exec, s[2:3]
	s_waitcnt vmcnt(15)
	v_lshlrev_b32_e32 v86, 16, v134
	v_and_b32_e32 v87, 0xffff0000, v134
	v_lshlrev_b32_e32 v88, 16, v135
	v_and_b32_e32 v89, 0xffff0000, v135
	v_pk_add_f32 v[80:81], v[80:81], v[88:89]
	v_pk_add_f32 v[78:79], v[78:79], v[86:87]
	v_lshlrev_b32_e32 v86, 16, v136
	v_and_b32_e32 v87, 0xffff0000, v136
	v_lshlrev_b32_e32 v88, 16, v137
	v_and_b32_e32 v89, 0xffff0000, v137
	v_pk_add_f32 v[88:89], v[76:77], v[88:89]
	v_pk_add_f32 v[76:77], v[74:75], v[86:87]
	v_mul_f32_e32 v74, v79, v79
	v_mul_f32_e32 v75, v81, v81
	v_fmac_f32_e32 v74, v78, v78
	v_fmac_f32_e32 v75, v80, v80
	v_add_f32_e32 v74, v74, v75
	v_mul_f32_e32 v75, v77, v77
	v_mul_f32_e32 v86, v89, v89
	v_fmac_f32_e32 v75, v76, v76
	v_fmac_f32_e32 v86, v88, v88
	v_add_f32_e32 v75, v75, v86
	v_add_f32_e32 v86, v74, v75
	v_cvt_pk_bf16_f32 v74, v78, v79
	v_cvt_pk_bf16_f32 v75, v80, v81
	s_waitcnt vmcnt(14)
	v_lshlrev_b32_e32 v78, 16, v130
	v_and_b32_e32 v79, 0xffff0000, v130
	v_lshlrev_b32_e32 v80, 16, v131
	v_and_b32_e32 v81, 0xffff0000, v131
	v_pk_add_f32 v[72:73], v[72:73], v[80:81]
	v_pk_add_f32 v[70:71], v[70:71], v[78:79]
	v_lshlrev_b32_e32 v78, 16, v132
	v_and_b32_e32 v79, 0xffff0000, v132
	v_lshlrev_b32_e32 v80, 16, v133
	v_and_b32_e32 v81, 0xffff0000, v133
	v_pk_add_f32 v[78:79], v[66:67], v[78:79]
	v_mul_f32_e32 v66, v71, v71
	v_mul_f32_e32 v67, v73, v73
	v_pk_add_f32 v[80:81], v[68:69], v[80:81]
	v_fmac_f32_e32 v66, v70, v70
	v_fmac_f32_e32 v67, v72, v72
	v_add_f32_e32 v66, v66, v67
	v_mul_f32_e32 v67, v79, v79
	v_mul_f32_e32 v68, v81, v81
	v_fmac_f32_e32 v67, v78, v78
	v_fmac_f32_e32 v68, v80, v80
	v_add_f32_e32 v67, v67, v68
	v_add_f32_e32 v66, v66, v67
	v_add_f32_e32 v66, v86, v66
	ds_bpermute_b32 v67, v181, v66
	s_mov_b64 s[2:3], 0x30000
	s_waitcnt lgkmcnt(1)
	v_lshl_add_u64 v[82:83], v[170:171], 0, s[2:3]
	s_mov_b64 s[2:3], 0x30400
	v_lshl_add_u64 v[84:85], v[170:171], 0, s[2:3]
	s_waitcnt lgkmcnt(0)
	v_add_f32_e32 v66, v66, v67
	ds_bpermute_b32 v67, v114, v66
	v_cvt_pk_bf16_f32 v76, v76, v77
	v_cvt_pk_bf16_f32 v77, v88, v89
	global_store_dwordx4 v[82:83], v[74:77], off
	v_cvt_pk_bf16_f32 v68, v70, v71
	v_cvt_pk_bf16_f32 v69, v72, v73
	v_cvt_pk_bf16_f32 v70, v78, v79
	v_cvt_pk_bf16_f32 v71, v80, v81
	global_store_dwordx4 v[84:85], v[68:71], off
	s_and_saveexec_b64 s[2:3], s[4:5]
	s_cbranch_execz .LBB0_2012
	s_waitcnt lgkmcnt(0)
	v_add_f32_e32 v66, v66, v67
	ds_write_b32 v180, v66 offset:768
.LBB0_2012:
	s_or_b64 exec, exec, s[2:3]
	v_add_co_u32_e32 v90, vcc, 0x80000, v170
	s_nop 1
	v_addc_co_u32_e32 v91, vcc, 0, v171, vcc
	s_nop 0
	s_nop 0
	v_add_co_u32_e32 v66, vcc, 0x90000, v170
	s_nop 0
	s_waitcnt vmcnt(15)
	v_lshlrev_b32_e32 v100, 16, v194
	s_waitcnt lgkmcnt(0)
	v_addc_co_u32_e32 v67, vcc, 0, v171, vcc
	v_add_co_u32_e32 v68, vcc, 0xa0000, v170
	s_nop 0
	s_nop 0
	v_addc_co_u32_e32 v69, vcc, 0, v171, vcc
	v_add_co_u32_e32 v66, vcc, 0xb0000, v170
	s_nop 0
	s_nop 0
	v_addc_co_u32_e32 v67, vcc, 0, v171, vcc
	s_nop 0
	s_nop 0
	s_nop 0
	v_and_b32_e32 v101, 0xffff0000, v194
	v_lshlrev_b32_e32 v92, 16, v195
	v_and_b32_e32 v93, 0xffff0000, v195
	v_lshlrev_b32_e32 v102, 16, v196
	v_and_b32_e32 v103, 0xffff0000, v196
	v_lshlrev_b32_e32 v94, 16, v197
	v_and_b32_e32 v95, 0xffff0000, v197
	s_nop 0
	s_waitcnt vmcnt(14)
	v_lshlrev_b32_e32 v104, 16, v198
	v_and_b32_e32 v105, 0xffff0000, v198
	v_lshlrev_b32_e32 v96, 16, v199
	v_and_b32_e32 v97, 0xffff0000, v199
	v_lshlrev_b32_e32 v106, 16, v200
	v_and_b32_e32 v107, 0xffff0000, v200
	v_lshlrev_b32_e32 v98, 16, v201
	v_and_b32_e32 v99, 0xffff0000, v201
	v_pk_add_f32 v[64:65], v[64:65], v[92:93]
	v_pk_add_f32 v[62:63], v[62:63], v[100:101]
	v_pk_add_f32 v[60:61], v[60:61], v[94:95]
	v_pk_add_f32 v[58:59], v[58:59], v[102:103]
	v_pk_add_f32 v[56:57], v[56:57], v[96:97]
	v_pk_add_f32 v[54:55], v[54:55], v[104:105]
	v_pk_add_f32 v[92:93], v[52:53], v[98:99]
	v_pk_add_f32 v[94:95], v[50:51], v[106:107]
	v_mul_f32_e32 v52, v63, v63
	v_mul_f32_e32 v53, v65, v65
	v_mul_f32_e32 v96, v59, v59
	v_mul_f32_e32 v97, v61, v61
	v_cvt_pk_bf16_f32 v50, v62, v63
	v_cvt_pk_bf16_f32 v51, v64, v65
	v_mul_f32_e32 v63, v55, v55
	v_mul_f32_e32 v65, v57, v57
	v_mul_f32_e32 v98, v95, v95
	v_mul_f32_e32 v99, v93, v93
	v_fmac_f32_e32 v52, v62, v62
	v_fmac_f32_e32 v53, v64, v64
	v_fmac_f32_e32 v96, v58, v58
	v_fmac_f32_e32 v97, v60, v60
	v_fmac_f32_e32 v63, v54, v54
	v_fmac_f32_e32 v65, v56, v56
	v_fmac_f32_e32 v98, v94, v94
	v_fmac_f32_e32 v99, v92, v92
	v_add_f32_e32 v52, v52, v53
	v_add_f32_e32 v53, v96, v97
	v_add_f32_e32 v62, v63, v65
	v_add_f32_e32 v63, v98, v99
	v_add_f32_e32 v52, v52, v53
	v_add_f32_e32 v53, v62, v63
	v_add_f32_e32 v62, v52, v53
	ds_bpermute_b32 v63, v181, v62
	v_cvt_pk_bf16_f32 v52, v58, v59
	v_cvt_pk_bf16_f32 v53, v60, v61
	global_store_dwordx4 v[90:91], v[50:53], off
	s_waitcnt lgkmcnt(0)
	s_nop 0
	v_add_f32_e32 v50, v62, v63
	ds_bpermute_b32 v51, v114, v50
	v_cvt_pk_bf16_f32 v52, v54, v55
	v_cvt_pk_bf16_f32 v53, v56, v57
	v_cvt_pk_bf16_f32 v54, v94, v95
	v_cvt_pk_bf16_f32 v55, v92, v93
	global_store_dwordx4 v[90:91], v[52:55], off offset:1024
	s_and_saveexec_b64 s[2:3], s[4:5]
	s_cbranch_execz .LBB0_2014
	s_waitcnt lgkmcnt(0)
	v_add_f32_e32 v50, v50, v51
	ds_write_b32 v180, v50 offset:2048
; __device__ __forceinline__ u32x4 pack8(f32x4 v0, f32x4 v1) { u32x4 w; w.x = cvt_pk_bf16(v0[0], v0[1]); w.y = cvt_pk_bf16(v0[2], v0[3]); w.z = cvt_pk_bf16(v1[0], v1[1]); w.w = cvt_pk_bf16(v1[2], v1[3]); return w; }
;     __device__ __forceinline__ void operator()(const f32x4 (&acc)[2][2][4][2], const Unit& u, int wr, int wc, int fr, int fq) const {
;     ...
;                     for (int bj = 0; bj < 2; ++bj) { const u32x4 o = old[m][bj];
;                         f32x4 x0 = (f32x4){__uint_as_float(o.x << 16), __uint_as_float(o.x & 0xffff0000u), __uint_as_float(o.y << 16), __uint_as_float(o.y & 0xffff0000u)} + acc[ai][bj][m][0];
;                         f32x4 x1 = (f32x4){__uint_as_float(o.z << 16), __uint_as_float(o.z & 0xffff0000u), __uint_as_float(o.w << 16), __uint_as_float(o.w & 0xffff0000u)} + acc[ai][bj][m][1];
;                         q += ((x0[0] * x0[0] + x0[1] * x0[1]) + (x0[2] * x0[2] + x0[3] * x0[3])) + ((x1[0] * x1[0] + x1[1] * x1[1]) + (x1[2] * x1[2] + x1[3] * x1[3]));
;                         *(u32x4*)(rowp + bj * 512) = pack8(x0, x1); }
;                     q += __shfl_xor(q, 16); q += __shfl_xor(q, 32);
;                     if (fq == 0) PL[rl * 4 + wc] = q; } }
.LBB0_2014:
	s_or_b64 exec, exec, s[2:3]
	s_nop 0
	s_waitcnt vmcnt(15)
	v_lshlrev_b32_e32 v54, 16, v202
	v_and_b32_e32 v55, 0xffff0000, v202
	v_lshlrev_b32_e32 v56, 16, v203
	v_and_b32_e32 v57, 0xffff0000, v203
	v_pk_add_f32 v[48:49], v[48:49], v[56:57]
	v_pk_add_f32 v[46:47], v[46:47], v[54:55]
	v_lshlrev_b32_e32 v54, 16, v204
	v_and_b32_e32 v55, 0xffff0000, v204
	v_lshlrev_b32_e32 v56, 16, v205
	v_and_b32_e32 v57, 0xffff0000, v205
	v_pk_add_f32 v[56:57], v[44:45], v[56:57]
	v_pk_add_f32 v[44:45], v[42:43], v[54:55]
	v_mul_f32_e32 v42, v47, v47
	v_mul_f32_e32 v43, v49, v49
	v_fmac_f32_e32 v42, v46, v46
	v_fmac_f32_e32 v43, v48, v48
	v_add_f32_e32 v42, v42, v43
	v_mul_f32_e32 v43, v45, v45
	v_mul_f32_e32 v54, v57, v57
	v_fmac_f32_e32 v43, v44, v44
	v_fmac_f32_e32 v54, v56, v56
	v_add_f32_e32 v43, v43, v54
	v_add_f32_e32 v54, v42, v43
	v_cvt_pk_bf16_f32 v42, v46, v47
	v_cvt_pk_bf16_f32 v43, v48, v49
	s_nop 0
	s_waitcnt vmcnt(14)
	v_lshlrev_b32_e32 v46, 16, v206
	v_and_b32_e32 v47, 0xffff0000, v206
	v_lshlrev_b32_e32 v48, 16, v207
	v_and_b32_e32 v49, 0xffff0000, v207
	v_pk_add_f32 v[40:41], v[40:41], v[48:49]
	v_pk_add_f32 v[38:39], v[38:39], v[46:47]
	v_lshlrev_b32_e32 v46, 16, v208
	v_and_b32_e32 v47, 0xffff0000, v208
	v_lshlrev_b32_e32 v48, 16, v209
	v_and_b32_e32 v49, 0xffff0000, v209
	v_pk_add_f32 v[46:47], v[34:35], v[46:47]
	v_mul_f32_e32 v34, v39, v39
	v_mul_f32_e32 v35, v41, v41
	v_pk_add_f32 v[48:49], v[36:37], v[48:49]
	v_fmac_f32_e32 v34, v38, v38
	v_fmac_f32_e32 v35, v40, v40
	v_add_f32_e32 v34, v34, v35
	v_mul_f32_e32 v35, v47, v47
	v_mul_f32_e32 v36, v49, v49
	v_fmac_f32_e32 v35, v46, v46
	v_fmac_f32_e32 v36, v48, v48
	v_add_f32_e32 v35, v35, v36
	v_add_f32_e32 v34, v34, v35
	v_add_f32_e32 v34, v54, v34
	ds_bpermute_b32 v35, v181, v34
	s_mov_b64 s[2:3], 0x90000
	s_waitcnt lgkmcnt(1)
	v_lshl_add_u64 v[50:51], v[170:171], 0, s[2:3]
	s_mov_b64 s[2:3], 0x90400
	v_lshl_add_u64 v[52:53], v[170:171], 0, s[2:3]
	s_waitcnt lgkmcnt(0)
	v_add_f32_e32 v34, v34, v35
	ds_bpermute_b32 v35, v114, v34
	v_cvt_pk_bf16_f32 v44, v44, v45
	v_cvt_pk_bf16_f32 v45, v56, v57
	global_store_dwordx4 v[50:51], v[42:45], off
	v_cvt_pk_bf16_f32 v36, v38, v39
	v_cvt_pk_bf16_f32 v37, v40, v41
	v_cvt_pk_bf16_f32 v38, v46, v47
	v_cvt_pk_bf16_f32 v39, v48, v49
	global_store_dwordx4 v[52:53], v[36:39], off
	s_and_saveexec_b64 s[2:3], s[4:5]
	s_cbranch_execz .LBB0_2016
	s_waitcnt lgkmcnt(0)
	v_add_f32_e32 v34, v34, v35
	ds_write_b32 v180, v34 offset:2304
; __device__ __forceinline__ u32x4 pack8(f32x4 v0, f32x4 v1) { u32x4 w; w.x = cvt_pk_bf16(v0[0], v0[1]); w.y = cvt_pk_bf16(v0[2], v0[3]); w.z = cvt_pk_bf16(v1[0], v1[1]); w.w = cvt_pk_bf16(v1[2], v1[3]); return w; }
;     __device__ __forceinline__ void operator()(const f32x4 (&acc)[2][2][4][2], const Unit& u, int wr, int wc, int fr, int fq) const {
;     ...
;                 for (int m = 0; m < 4; ++m) { const int rl = ai * HALF + wr * 64 + m * 16 + fr; bf16_t* rowp = xbb + (size_t)(ai * 8 + m) * 64 * 512; float q = 0.f;
; #pragma unroll
;                     for (int bj = 0; bj < 2; ++bj) { const u32x4 o = old[m][bj];
;                         f32x4 x0 = (f32x4){__uint_as_float(o.x << 16), __uint_as_float(o.x & 0xffff0000u), __uint_as_float(o.y << 16), __uint_as_float(o.y & 0xffff0000u)} + acc[ai][bj][m][0];
;                         f32x4 x1 = (f32x4){__uint_as_float(o.z << 16), __uint_as_float(o.z & 0xffff0000u), __uint_as_float(o.w << 16), __uint_as_float(o.w & 0xffff0000u)} + acc[ai][bj][m][1];
;                         q += ((x0[0] * x0[0] + x0[1] * x0[1]) + (x0[2] * x0[2] + x0[3] * x0[3])) + ((x1[0] * x1[0] + x1[1] * x1[1]) + (x1[2] * x1[2] + x1[3] * x1[3]));
;                         *(u32x4*)(rowp + bj * 512) = pack8(x0, x1); }
;                     q += __shfl_xor(q, 16); q += __shfl_xor(q, 32);
;                     if (fq == 0) PL[rl * 4 + wc] = q; } }
.LBB0_2016:
	s_or_b64 exec, exec, s[2:3]
	s_nop 0
	s_waitcnt vmcnt(15)
	v_lshlrev_b32_e32 v38, 16, v210
	v_and_b32_e32 v39, 0xffff0000, v210
	v_lshlrev_b32_e32 v40, 16, v211
	v_and_b32_e32 v41, 0xffff0000, v211
	v_pk_add_f32 v[32:33], v[32:33], v[40:41]
	v_pk_add_f32 v[30:31], v[30:31], v[38:39]
	v_lshlrev_b32_e32 v38, 16, v212
	v_and_b32_e32 v39, 0xffff0000, v212
	v_lshlrev_b32_e32 v40, 16, v213
	v_and_b32_e32 v41, 0xffff0000, v213
	v_pk_add_f32 v[40:41], v[28:29], v[40:41]
	v_pk_add_f32 v[28:29], v[26:27], v[38:39]
	v_mul_f32_e32 v26, v31, v31
	v_mul_f32_e32 v27, v33, v33
	v_fmac_f32_e32 v26, v30, v30
	v_fmac_f32_e32 v27, v32, v32
	v_add_f32_e32 v26, v26, v27
	v_mul_f32_e32 v27, v29, v29
	v_mul_f32_e32 v38, v41, v41
	v_fmac_f32_e32 v27, v28, v28
	v_fmac_f32_e32 v38, v40, v40
	v_add_f32_e32 v27, v27, v38
	v_add_f32_e32 v38, v26, v27
	v_cvt_pk_bf16_f32 v26, v30, v31
	v_cvt_pk_bf16_f32 v27, v32, v33
	s_nop 0
	s_waitcnt vmcnt(14)
	v_lshlrev_b32_e32 v30, 16, v214
	v_and_b32_e32 v31, 0xffff0000, v214
	v_lshlrev_b32_e32 v32, 16, v215
	v_and_b32_e32 v33, 0xffff0000, v215
	v_pk_add_f32 v[24:25], v[24:25], v[32:33]
	v_pk_add_f32 v[22:23], v[22:23], v[30:31]
	v_lshlrev_b32_e32 v30, 16, v216
	v_and_b32_e32 v31, 0xffff0000, v216
	v_lshlrev_b32_e32 v32, 16, v217
	v_and_b32_e32 v33, 0xffff0000, v217
	v_pk_add_f32 v[30:31], v[18:19], v[30:31]
	v_mul_f32_e32 v18, v23, v23
	v_mul_f32_e32 v19, v25, v25
	v_pk_add_f32 v[32:33], v[20:21], v[32:33]
	v_fmac_f32_e32 v18, v22, v22
	v_fmac_f32_e32 v19, v24, v24
	v_add_f32_e32 v18, v18, v19
	v_mul_f32_e32 v19, v31, v31
	v_mul_f32_e32 v20, v33, v33
	v_fmac_f32_e32 v19, v30, v30
	v_fmac_f32_e32 v20, v32, v32
	v_add_f32_e32 v19, v19, v20
	v_add_f32_e32 v18, v18, v19
	v_add_f32_e32 v18, v38, v18
	ds_bpermute_b32 v19, v181, v18
	s_mov_b64 s[2:3], 0xa0000
	s_waitcnt lgkmcnt(1)
	v_lshl_add_u64 v[34:35], v[170:171], 0, s[2:3]
	s_mov_b64 s[2:3], 0xa0400
	v_lshl_add_u64 v[36:37], v[170:171], 0, s[2:3]
	s_waitcnt lgkmcnt(0)
	v_add_f32_e32 v18, v18, v19
	ds_bpermute_b32 v19, v114, v18
	v_cvt_pk_bf16_f32 v28, v28, v29
	v_cvt_pk_bf16_f32 v29, v40, v41
	global_store_dwordx4 v[34:35], v[26:29], off
	v_cvt_pk_bf16_f32 v20, v22, v23
	v_cvt_pk_bf16_f32 v21, v24, v25
	v_cvt_pk_bf16_f32 v22, v30, v31
	v_cvt_pk_bf16_f32 v23, v32, v33
	global_store_dwordx4 v[36:37], v[20:23], off
	s_and_saveexec_b64 s[2:3], s[4:5]
	s_cbranch_execz .LBB0_2018
	s_waitcnt lgkmcnt(0)
	v_add_f32_e32 v18, v18, v19
	ds_write_b32 v180, v18 offset:2560
.LBB0_2018:
	s_or_b64 exec, exec, s[2:3]
	s_nop 0
	s_waitcnt vmcnt(15)
	v_lshlrev_b32_e32 v22, 16, v218
	v_and_b32_e32 v23, 0xffff0000, v218
	v_lshlrev_b32_e32 v24, 16, v219
	v_and_b32_e32 v25, 0xffff0000, v219
	v_pk_add_f32 v[16:17], v[16:17], v[24:25]
	v_pk_add_f32 v[14:15], v[14:15], v[22:23]
	v_lshlrev_b32_e32 v22, 16, v220
	v_and_b32_e32 v23, 0xffff0000, v220
	v_lshlrev_b32_e32 v24, 16, v221
	v_and_b32_e32 v25, 0xffff0000, v221
	v_pk_add_f32 v[24:25], v[12:13], v[24:25]
	v_pk_add_f32 v[12:13], v[10:11], v[22:23]
	v_mul_f32_e32 v10, v15, v15
	v_mul_f32_e32 v11, v17, v17
	v_fmac_f32_e32 v10, v14, v14
	v_fmac_f32_e32 v11, v16, v16
	v_add_f32_e32 v10, v10, v11
	v_mul_f32_e32 v11, v13, v13
	v_mul_f32_e32 v22, v25, v25
	v_fmac_f32_e32 v11, v12, v12
	v_fmac_f32_e32 v22, v24, v24
	v_add_f32_e32 v11, v11, v22
	v_add_f32_e32 v22, v10, v11
	v_cvt_pk_bf16_f32 v10, v14, v15
	v_cvt_pk_bf16_f32 v11, v16, v17
	s_nop 0
	s_waitcnt vmcnt(14)
	v_lshlrev_b32_e32 v14, 16, v222
	v_and_b32_e32 v15, 0xffff0000, v222
	v_lshlrev_b32_e32 v16, 16, v223
	v_and_b32_e32 v17, 0xffff0000, v223
	v_pk_add_f32 v[8:9], v[8:9], v[16:17]
	v_pk_add_f32 v[6:7], v[6:7], v[14:15]
	v_lshlrev_b32_e32 v14, 16, v224
	v_and_b32_e32 v15, 0xffff0000, v224
	v_lshlrev_b32_e32 v16, 16, v225
	v_and_b32_e32 v17, 0xffff0000, v225
	v_pk_add_f32 v[14:15], v[2:3], v[14:15]
	v_mul_f32_e32 v2, v7, v7
	v_mul_f32_e32 v3, v9, v9
	v_pk_add_f32 v[16:17], v[4:5], v[16:17]
	v_fmac_f32_e32 v2, v6, v6
	v_fmac_f32_e32 v3, v8, v8
	v_add_f32_e32 v2, v2, v3
	v_mul_f32_e32 v3, v15, v15
	v_mul_f32_e32 v4, v17, v17
	v_fmac_f32_e32 v3, v14, v14
	v_fmac_f32_e32 v4, v16, v16
	v_add_f32_e32 v3, v3, v4
	v_add_f32_e32 v2, v2, v3
	v_add_f32_e32 v2, v22, v2
	ds_bpermute_b32 v3, v181, v2
	s_mov_b64 s[2:3], 0xb0000
	s_waitcnt lgkmcnt(1)
	v_lshl_add_u64 v[18:19], v[170:171], 0, s[2:3]
	v_lshl_add_u64 v[20:21], v[170:171], 0, s[36:37]
	v_cvt_pk_bf16_f32 v12, v12, v13
	s_waitcnt lgkmcnt(0)
	v_add_f32_e32 v2, v2, v3
	ds_bpermute_b32 v3, v114, v2
	v_cvt_pk_bf16_f32 v13, v24, v25
	global_store_dwordx4 v[18:19], v[10:13], off
	v_cvt_pk_bf16_f32 v4, v6, v7
	v_cvt_pk_bf16_f32 v5, v8, v9
	v_cvt_pk_bf16_f32 v6, v14, v15
	v_cvt_pk_bf16_f32 v7, v16, v17
	global_store_dwordx4 v[20:21], v[4:7], off
	s_and_saveexec_b64 s[2:3], s[4:5]
	s_cbranch_execz .LBB0_2020
	s_waitcnt lgkmcnt(0)
	v_add_f32_e32 v2, v2, v3
	ds_write_b32 v180, v2 offset:2816

; #define PG8_LAS __attribute__((address_space(3)))
; __device__ __forceinline__ u32x4 pack8(f32x4 v0, f32x4 v1) { u32x4 w; w.x = cvt_pk_bf16(v0[0], v0[1]); w.y = cvt_pk_bf16(v0[2], v0[3]); w.z = cvt_pk_bf16(v1[0], v1[1]); w.w = cvt_pk_bf16(v1[2], v1[3]); return w; }
;     __device__ __forceinline__ void operator()(const f32x4 (&acc)[2][2][4][2], const Unit& u, int wr, int wc, int fr, int fq) const {
;     ...
;             bf16_t* xbb = XB + ((size_t)(u.pm * 16 + wr * 4) * 64 + u.pn * 8 + 2 * wc) * 512 + fr * 32 + (((fq * 16) ^ ((fr >> 3) << 5)) >> 1);
;             PG8_LAS float* PL = (PG8_LAS float*)xl;
; #pragma unroll
;             for (int ai = 0; ai < 2; ++ai) {
;                 u32x4 old[4][2];
; #pragma unroll
;                 for (int m = 0; m < 4; ++m)
; #pragma unroll
;                     for (int bj = 0; bj < 2; ++bj) old[m][bj] = *(const u32x4*)(xbb + ((size_t)(ai * 8 + m) * 64 + bj) * 512);
; #pragma unroll
;                 for (int m = 0; m < 4; ++m) { const int rl = ai * HALF + wr * 64 + m * 16 + fr; bf16_t* rowp = xbb + (size_t)(ai * 8 + m) * 64 * 512; float q = 0.f;
; #pragma unroll
;                     for (int bj = 0; bj < 2; ++bj) { const u32x4 o = old[m][bj];
;                         f32x4 x0 = (f32x4){__uint_as_float(o.x << 16), __uint_as_float(o.x & 0xffff0000u), __uint_as_float(o.y << 16), __uint_as_float(o.y & 0xffff0000u)} + acc[ai][bj][m][0];
;                         f32x4 x1 = (f32x4){__uint_as_float(o.z << 16), __uint_as_float(o.z & 0xffff0000u), __uint_as_float(o.w << 16), __uint_as_float(o.w & 0xffff0000u)} + acc[ai][bj][m][1];
;                         q += ((x0[0] * x0[0] + x0[1] * x0[1]) + (x0[2] * x0[2] + x0[3] * x0[3])) + ((x1[0] * x1[0] + x1[1] * x1[1]) + (x1[2] * x1[2] + x1[3] * x1[3]));
;                         *(u32x4*)(rowp + bj * 512) = pack8(x0, x1); }
;                     q += __shfl_xor(q, 16); q += __shfl_xor(q, 32);
;                     if (fq == 0) PL[rl * 4 + wc] = q; } }
.LBB0_2406:
	s_lshl_b32 s2, s2, 4
	s_add_i32 s2, s2, s77
	s_ashr_i32 s3, s2, 31
	s_lshl_b32 s49, s10, 3
	s_lshl_b64 s[2:3], s[2:3], 6
	s_ashr_i32 s53, s49, 31
	s_add_u32 s2, s2, s49
	s_addc_u32 s3, s3, s53
	s_or_b64 s[2:3], s[2:3], s[20:21]
	s_lshl_b64 s[2:3], s[2:3], 10
	v_lshl_add_u64 v[170:171], v[164:165], 0, s[2:3]
	global_load_dwordx4 v[158:161], v[170:171], off
	global_load_dwordx4 v[154:157], v[170:171], off offset:1024
	s_mov_b32 s2, 0x10000
	v_add_co_u32_e32 v130, vcc, s2, v170
	s_mov_b32 s3, 0x30000
	s_nop 0
	v_addc_co_u32_e32 v131, vcc, 0, v171, vcc
	v_add_co_u32_e32 v132, vcc, s82, v170
	global_load_dwordx4 v[150:153], v[130:131], off
	global_load_dwordx4 v[146:149], v[130:131], off offset:1024
	v_addc_co_u32_e32 v133, vcc, 0, v171, vcc
	v_add_co_u32_e32 v130, vcc, s3, v170
	global_load_dwordx4 v[142:145], v[132:133], off
	global_load_dwordx4 v[138:141], v[132:133], off offset:1024
	v_addc_co_u32_e32 v131, vcc, 0, v171, vcc
	global_load_dwordx4 v[134:137], v[130:131], off
	s_nop 0
	global_load_dwordx4 v[130:133], v[130:131], off offset:1024
	v_add_co_u32_e32 v226, vcc, 0x80000, v170
	s_nop 1
	v_addc_co_u32_e32 v227, vcc, 0, v171, vcc
	global_load_dwordx4 v[194:197], v[226:227], off
	global_load_dwordx4 v[198:201], v[226:227], off offset:1024
	v_add_co_u32_e32 v226, vcc, 0x90000, v170
	s_nop 1
	v_addc_co_u32_e32 v227, vcc, 0, v171, vcc
	global_load_dwordx4 v[202:205], v[226:227], off
	global_load_dwordx4 v[206:209], v[226:227], off offset:1024
	v_add_co_u32_e32 v226, vcc, 0xa0000, v170
	s_nop 1
	v_addc_co_u32_e32 v227, vcc, 0, v171, vcc
	global_load_dwordx4 v[210:213], v[226:227], off
	global_load_dwordx4 v[214:217], v[226:227], off offset:1024
	v_add_co_u32_e32 v226, vcc, 0xb0000, v170
	s_nop 1
	v_addc_co_u32_e32 v227, vcc, 0, v171, vcc
	global_load_dwordx4 v[218:221], v[226:227], off
	global_load_dwordx4 v[222:225], v[226:227], off offset:1024
	v_and_b32_e32 v183, 64, v179
	v_xor_b32_e32 v181, 16, v179
	v_add_u32_e32 v183, 64, v183
	v_xor_b32_e32 v184, 32, v179
	v_cmp_lt_i32_e32 vcc, v181, v183
	s_nop 0
	s_waitcnt vmcnt(15)
	v_and_b32_e32 v185, 0xffff0000, v158
	v_cndmask_b32_e32 v181, v179, v181, vcc
	v_cmp_lt_i32_e32 vcc, v184, v183
	v_lshlrev_b32_e32 v186, 16, v160
	v_and_b32_e32 v187, 0xffff0000, v160
	v_cndmask_b32_e32 v183, v179, v184, vcc
	v_lshlrev_b32_e32 v184, 16, v158
	v_lshlrev_b32_e32 v158, 16, v159
	v_and_b32_e32 v159, 0xffff0000, v159
	v_lshlrev_b32_e32 v160, 16, v161
	v_and_b32_e32 v161, 0xffff0000, v161
	s_waitcnt vmcnt(14)
	v_lshlrev_b32_e32 v188, 16, v154
	v_and_b32_e32 v189, 0xffff0000, v154
	v_lshlrev_b32_e32 v154, 16, v155
	v_and_b32_e32 v155, 0xffff0000, v155
	v_lshlrev_b32_e32 v190, 16, v156
	v_and_b32_e32 v191, 0xffff0000, v156
	v_lshlrev_b32_e32 v156, 16, v157
	v_and_b32_e32 v157, 0xffff0000, v157
	v_pk_add_f32 v[128:129], v[128:129], v[158:159]
	v_pk_add_f32 v[126:127], v[126:127], v[184:185]
	v_pk_add_f32 v[124:125], v[124:125], v[160:161]
	v_pk_add_f32 v[122:123], v[122:123], v[186:187]
	v_pk_add_f32 v[120:121], v[120:121], v[154:155]
	v_pk_add_f32 v[118:119], v[118:119], v[188:189]
	v_pk_add_f32 v[154:155], v[116:117], v[156:157]
	v_pk_add_f32 v[156:157], v[114:115], v[190:191]
	v_mul_f32_e32 v116, v127, v127
	v_mul_f32_e32 v117, v129, v129
	v_mul_f32_e32 v158, v123, v123
	v_mul_f32_e32 v159, v125, v125
	v_cvt_pk_bf16_f32 v114, v126, v127
	v_cvt_pk_bf16_f32 v115, v128, v129
	v_mul_f32_e32 v127, v119, v119
	v_mul_f32_e32 v129, v121, v121
	v_mul_f32_e32 v160, v157, v157
	v_mul_f32_e32 v161, v155, v155
	v_fmac_f32_e32 v116, v126, v126
	v_fmac_f32_e32 v117, v128, v128
	v_fmac_f32_e32 v158, v122, v122
	v_fmac_f32_e32 v159, v124, v124
	v_fmac_f32_e32 v127, v118, v118
	v_fmac_f32_e32 v129, v120, v120
	v_fmac_f32_e32 v160, v156, v156
	v_fmac_f32_e32 v161, v154, v154
	v_add_f32_e32 v116, v116, v117
	v_add_f32_e32 v117, v158, v159
	v_add_f32_e32 v126, v127, v129
	v_add_f32_e32 v127, v160, v161
	v_add_f32_e32 v116, v116, v117
	v_add_f32_e32 v117, v126, v127
	v_lshlrev_b32_e32 v181, 2, v181
	v_add_f32_e32 v126, v116, v117
	ds_bpermute_b32 v127, v181, v126
	v_cvt_pk_bf16_f32 v116, v122, v123
	v_cvt_pk_bf16_f32 v117, v124, v125
	global_store_dwordx4 v[170:171], v[114:117], off
	v_cvt_pk_bf16_f32 v118, v118, v119
	v_cvt_pk_bf16_f32 v119, v120, v121
	v_cvt_pk_bf16_f32 v120, v156, v157
	v_cvt_pk_bf16_f32 v121, v154, v155
	global_store_dwordx4 v[170:171], v[118:121], off offset:1024
	s_waitcnt lgkmcnt(0)
	v_add_f32_e32 v115, v126, v127
	v_lshlrev_b32_e32 v114, 2, v183
	ds_bpermute_b32 v116, v114, v115
	s_and_saveexec_b64 s[2:3], s[4:5]
	s_cbranch_execz .LBB0_2408
	s_waitcnt lgkmcnt(0)
	v_add_f32_e32 v115, v115, v116
	ds_write_b32 v180, v115

; __device__ __forceinline__ u32x4 pack8(f32x4 v0, f32x4 v1) { u32x4 w; w.x = cvt_pk_bf16(v0[0], v0[1]); w.y = cvt_pk_bf16(v0[2], v0[3]); w.z = cvt_pk_bf16(v1[0], v1[1]); w.w = cvt_pk_bf16(v1[2], v1[3]); return w; }
;     __device__ __forceinline__ void operator()(const f32x4 (&acc)[2][2][4][2], const Unit& u, int wr, int wc, int fr, int fq) const {
;     ...
;                     for (int bj = 0; bj < 2; ++bj) { const u32x4 o = old[m][bj];
;                         f32x4 x0 = (f32x4){__uint_as_float(o.x << 16), __uint_as_float(o.x & 0xffff0000u), __uint_as_float(o.y << 16), __uint_as_float(o.y & 0xffff0000u)} + acc[ai][bj][m][0];
;                         f32x4 x1 = (f32x4){__uint_as_float(o.z << 16), __uint_as_float(o.z & 0xffff0000u), __uint_as_float(o.w << 16), __uint_as_float(o.w & 0xffff0000u)} + acc[ai][bj][m][1];
;                         q += ((x0[0] * x0[0] + x0[1] * x0[1]) + (x0[2] * x0[2] + x0[3] * x0[3])) + ((x1[0] * x1[0] + x1[1] * x1[1]) + (x1[2] * x1[2] + x1[3] * x1[3]));
;                         *(u32x4*)(rowp + bj * 512) = pack8(x0, x1); }
;                     q += __shfl_xor(q, 16); q += __shfl_xor(q, 32);
;                     if (fq == 0) PL[rl * 4 + wc] = q; } }
.LBB0_2416:
	s_or_b64 exec, exec, s[2:3]
	s_nop 0
	s_waitcnt vmcnt(15)
	v_lshlrev_b32_e32 v54, 16, v202
	v_and_b32_e32 v55, 0xffff0000, v202
	v_lshlrev_b32_e32 v56, 16, v203
	v_and_b32_e32 v57, 0xffff0000, v203
	v_pk_add_f32 v[48:49], v[48:49], v[56:57]
	v_pk_add_f32 v[46:47], v[46:47], v[54:55]
	v_lshlrev_b32_e32 v54, 16, v204
	v_and_b32_e32 v55, 0xffff0000, v204
	v_lshlrev_b32_e32 v56, 16, v205
	v_and_b32_e32 v57, 0xffff0000, v205
	v_pk_add_f32 v[56:57], v[44:45], v[56:57]
	v_pk_add_f32 v[44:45], v[42:43], v[54:55]
	v_mul_f32_e32 v42, v47, v47
	v_mul_f32_e32 v43, v49, v49
	v_fmac_f32_e32 v42, v46, v46
	v_fmac_f32_e32 v43, v48, v48
	v_add_f32_e32 v42, v42, v43
	v_mul_f32_e32 v43, v45, v45
	v_mul_f32_e32 v54, v57, v57
	v_fmac_f32_e32 v43, v44, v44
	v_fmac_f32_e32 v54, v56, v56
	v_add_f32_e32 v43, v43, v54
	v_add_f32_e32 v54, v42, v43
	v_cvt_pk_bf16_f32 v42, v46, v47
	v_cvt_pk_bf16_f32 v43, v48, v49
	s_nop 0
	s_waitcnt vmcnt(14)
	v_lshlrev_b32_e32 v46, 16, v206
	v_and_b32_e32 v47, 0xffff0000, v206
	v_lshlrev_b32_e32 v48, 16, v207
	v_and_b32_e32 v49, 0xffff0000, v207
	v_pk_add_f32 v[40:41], v[40:41], v[48:49]
	v_pk_add_f32 v[38:39], v[38:39], v[46:47]
	v_lshlrev_b32_e32 v46, 16, v208
	v_and_b32_e32 v47, 0xffff0000, v208
	v_lshlrev_b32_e32 v48, 16, v209
	v_and_b32_e32 v49, 0xffff0000, v209
	v_pk_add_f32 v[46:47], v[34:35], v[46:47]
	v_mul_f32_e32 v34, v39, v39
	v_mul_f32_e32 v35, v41, v41
	v_pk_add_f32 v[48:49], v[36:37], v[48:49]
	v_fmac_f32_e32 v34, v38, v38
	v_fmac_f32_e32 v35, v40, v40
	v_add_f32_e32 v34, v34, v35
	v_mul_f32_e32 v35, v47, v47
	v_mul_f32_e32 v36, v49, v49
	v_fmac_f32_e32 v35, v46, v46
	v_fmac_f32_e32 v36, v48, v48
	v_add_f32_e32 v35, v35, v36
	v_add_f32_e32 v34, v34, v35
	v_add_f32_e32 v34, v54, v34
	ds_bpermute_b32 v35, v181, v34
	s_waitcnt lgkmcnt(1)
	v_lshl_add_u64 v[50:51], v[170:171], 0, s[36:37]
	v_lshl_add_u64 v[52:53], v[170:171], 0, s[38:39]
	v_cvt_pk_bf16_f32 v44, v44, v45
	v_cvt_pk_bf16_f32 v45, v56, v57
	s_waitcnt lgkmcnt(0)
	v_add_f32_e32 v34, v34, v35
	ds_bpermute_b32 v35, v114, v34
	global_store_dwordx4 v[50:51], v[42:45], off
	v_cvt_pk_bf16_f32 v36, v38, v39
	v_cvt_pk_bf16_f32 v37, v40, v41
	v_cvt_pk_bf16_f32 v38, v46, v47
	v_cvt_pk_bf16_f32 v39, v48, v49
	global_store_dwordx4 v[52:53], v[36:39], off
	s_and_saveexec_b64 s[2:3], s[4:5]
	s_cbranch_execz .LBB0_2418
	s_waitcnt lgkmcnt(0)
	v_add_f32_e32 v34, v34, v35
	ds_write_b32 v180, v34 offset:2304
; __device__ __forceinline__ u32x4 pack8(f32x4 v0, f32x4 v1) { u32x4 w; w.x = cvt_pk_bf16(v0[0], v0[1]); w.y = cvt_pk_bf16(v0[2], v0[3]); w.z = cvt_pk_bf16(v1[0], v1[1]); w.w = cvt_pk_bf16(v1[2], v1[3]); return w; }
;     __device__ __forceinline__ void operator()(const f32x4 (&acc)[2][2][4][2], const Unit& u, int wr, int wc, int fr, int fq) const {
;     ...
;                 for (int m = 0; m < 4; ++m) { const int rl = ai * HALF + wr * 64 + m * 16 + fr; bf16_t* rowp = xbb + (size_t)(ai * 8 + m) * 64 * 512; float q = 0.f;
; #pragma unroll
;                     for (int bj = 0; bj < 2; ++bj) { const u32x4 o = old[m][bj];
;                         f32x4 x0 = (f32x4){__uint_as_float(o.x << 16), __uint_as_float(o.x & 0xffff0000u), __uint_as_float(o.y << 16), __uint_as_float(o.y & 0xffff0000u)} + acc[ai][bj][m][0];
;                         f32x4 x1 = (f32x4){__uint_as_float(o.z << 16), __uint_as_float(o.z & 0xffff0000u), __uint_as_float(o.w << 16), __uint_as_float(o.w & 0xffff0000u)} + acc[ai][bj][m][1];
;                         q += ((x0[0] * x0[0] + x0[1] * x0[1]) + (x0[2] * x0[2] + x0[3] * x0[3])) + ((x1[0] * x1[0] + x1[1] * x1[1]) + (x1[2] * x1[2] + x1[3] * x1[3]));
;                         *(u32x4*)(rowp + bj * 512) = pack8(x0, x1); }
;                     q += __shfl_xor(q, 16); q += __shfl_xor(q, 32);
;                     if (fq == 0) PL[rl * 4 + wc] = q; } }
.LBB0_2418:
	s_or_b64 exec, exec, s[2:3]
	s_nop 0
	s_waitcnt vmcnt(15)
	v_lshlrev_b32_e32 v38, 16, v210
	v_and_b32_e32 v39, 0xffff0000, v210
	v_lshlrev_b32_e32 v40, 16, v211
	v_and_b32_e32 v41, 0xffff0000, v211
	v_pk_add_f32 v[32:33], v[32:33], v[40:41]
	v_pk_add_f32 v[30:31], v[30:31], v[38:39]
	v_lshlrev_b32_e32 v38, 16, v212
	v_and_b32_e32 v39, 0xffff0000, v212
	v_lshlrev_b32_e32 v40, 16, v213
	v_and_b32_e32 v41, 0xffff0000, v213
	v_pk_add_f32 v[40:41], v[28:29], v[40:41]
	v_pk_add_f32 v[28:29], v[26:27], v[38:39]
	v_mul_f32_e32 v26, v31, v31
	v_mul_f32_e32 v27, v33, v33
	v_fmac_f32_e32 v26, v30, v30
	v_fmac_f32_e32 v27, v32, v32
	v_add_f32_e32 v26, v26, v27
	v_mul_f32_e32 v27, v29, v29
	v_mul_f32_e32 v38, v41, v41
	v_fmac_f32_e32 v27, v28, v28
	v_fmac_f32_e32 v38, v40, v40
	v_add_f32_e32 v27, v27, v38
	v_add_f32_e32 v38, v26, v27
	v_cvt_pk_bf16_f32 v26, v30, v31
	v_cvt_pk_bf16_f32 v27, v32, v33
	s_nop 0
	s_waitcnt vmcnt(14)
	v_lshlrev_b32_e32 v30, 16, v214
	v_and_b32_e32 v31, 0xffff0000, v214
	v_lshlrev_b32_e32 v32, 16, v215
	v_and_b32_e32 v33, 0xffff0000, v215
	v_pk_add_f32 v[24:25], v[24:25], v[32:33]
	v_pk_add_f32 v[22:23], v[22:23], v[30:31]
	v_lshlrev_b32_e32 v30, 16, v216
	v_and_b32_e32 v31, 0xffff0000, v216
	v_lshlrev_b32_e32 v32, 16, v217
	v_and_b32_e32 v33, 0xffff0000, v217
	v_pk_add_f32 v[30:31], v[18:19], v[30:31]
	v_mul_f32_e32 v18, v23, v23
	v_mul_f32_e32 v19, v25, v25
	v_pk_add_f32 v[32:33], v[20:21], v[32:33]
	v_fmac_f32_e32 v18, v22, v22
	v_fmac_f32_e32 v19, v24, v24
	v_add_f32_e32 v18, v18, v19
	v_mul_f32_e32 v19, v31, v31
	v_mul_f32_e32 v20, v33, v33
	v_fmac_f32_e32 v19, v30, v30
	v_fmac_f32_e32 v20, v32, v32
	v_add_f32_e32 v19, v19, v20
	v_add_f32_e32 v18, v18, v19
	v_add_f32_e32 v18, v38, v18
	ds_bpermute_b32 v19, v181, v18
	s_waitcnt lgkmcnt(1)
	v_lshl_add_u64 v[34:35], v[170:171], 0, s[40:41]
	v_lshl_add_u64 v[36:37], v[170:171], 0, s[42:43]
	v_cvt_pk_bf16_f32 v28, v28, v29
	v_cvt_pk_bf16_f32 v29, v40, v41
	s_waitcnt lgkmcnt(0)
	v_add_f32_e32 v18, v18, v19
	ds_bpermute_b32 v19, v114, v18
	global_store_dwordx4 v[34:35], v[26:29], off
	v_cvt_pk_bf16_f32 v20, v22, v23
	v_cvt_pk_bf16_f32 v21, v24, v25
	v_cvt_pk_bf16_f32 v22, v30, v31
	v_cvt_pk_bf16_f32 v23, v32, v33
	global_store_dwordx4 v[36:37], v[20:23], off
	s_and_saveexec_b64 s[2:3], s[4:5]
	s_cbranch_execz .LBB0_2420
	s_waitcnt lgkmcnt(0)
	v_add_f32_e32 v18, v18, v19
	ds_write_b32 v180, v18 offset:2560
.LBB0_2420:
	s_or_b64 exec, exec, s[2:3]
	s_nop 0
	s_waitcnt vmcnt(15)
	v_lshlrev_b32_e32 v22, 16, v218
	v_and_b32_e32 v23, 0xffff0000, v218
	v_lshlrev_b32_e32 v24, 16, v219
	v_and_b32_e32 v25, 0xffff0000, v219
	v_pk_add_f32 v[16:17], v[16:17], v[24:25]
	v_pk_add_f32 v[14:15], v[14:15], v[22:23]
	v_lshlrev_b32_e32 v22, 16, v220
	v_and_b32_e32 v23, 0xffff0000, v220
	v_lshlrev_b32_e32 v24, 16, v221
	v_and_b32_e32 v25, 0xffff0000, v221
	v_pk_add_f32 v[24:25], v[12:13], v[24:25]
	v_pk_add_f32 v[12:13], v[10:11], v[22:23]
	v_mul_f32_e32 v10, v15, v15
	v_mul_f32_e32 v11, v17, v17
	v_fmac_f32_e32 v10, v14, v14
	v_fmac_f32_e32 v11, v16, v16
	v_add_f32_e32 v10, v10, v11
	v_mul_f32_e32 v11, v13, v13
	v_mul_f32_e32 v22, v25, v25
	v_fmac_f32_e32 v11, v12, v12
	v_fmac_f32_e32 v22, v24, v24
	v_add_f32_e32 v11, v11, v22
	v_add_f32_e32 v22, v10, v11
	v_cvt_pk_bf16_f32 v10, v14, v15
	v_cvt_pk_bf16_f32 v11, v16, v17
	s_nop 0
	s_waitcnt vmcnt(14)
	v_lshlrev_b32_e32 v14, 16, v222
	v_and_b32_e32 v15, 0xffff0000, v222
	v_lshlrev_b32_e32 v16, 16, v223
	v_and_b32_e32 v17, 0xffff0000, v223
	v_pk_add_f32 v[8:9], v[8:9], v[16:17]
	v_pk_add_f32 v[6:7], v[6:7], v[14:15]
	v_lshlrev_b32_e32 v14, 16, v224
	v_and_b32_e32 v15, 0xffff0000, v224
	v_lshlrev_b32_e32 v16, 16, v225
	v_and_b32_e32 v17, 0xffff0000, v225
	v_pk_add_f32 v[14:15], v[2:3], v[14:15]
	v_mul_f32_e32 v2, v7, v7
	v_mul_f32_e32 v3, v9, v9
	v_pk_add_f32 v[16:17], v[4:5], v[16:17]
	v_fmac_f32_e32 v2, v6, v6
	v_fmac_f32_e32 v3, v8, v8
	v_add_f32_e32 v2, v2, v3
	v_mul_f32_e32 v3, v15, v15
	v_mul_f32_e32 v4, v17, v17
	v_fmac_f32_e32 v3, v14, v14
	v_fmac_f32_e32 v4, v16, v16
	v_add_f32_e32 v3, v3, v4
	v_add_f32_e32 v2, v2, v3
	v_add_f32_e32 v2, v22, v2
	ds_bpermute_b32 v3, v181, v2
	s_waitcnt lgkmcnt(1)
	v_lshl_add_u64 v[18:19], v[170:171], 0, s[44:45]
	v_lshl_add_u64 v[20:21], v[170:171], 0, s[46:47]
	v_cvt_pk_bf16_f32 v12, v12, v13
	v_cvt_pk_bf16_f32 v13, v24, v25
	s_waitcnt lgkmcnt(0)
	v_add_f32_e32 v2, v2, v3
	ds_bpermute_b32 v3, v114, v2
	global_store_dwordx4 v[18:19], v[10:13], off
	v_cvt_pk_bf16_f32 v4, v6, v7
	v_cvt_pk_bf16_f32 v5, v8, v9
	v_cvt_pk_bf16_f32 v6, v14, v15
	v_cvt_pk_bf16_f32 v7, v16, v17
	global_store_dwordx4 v[20:21], v[4:7], off
	s_and_saveexec_b64 s[2:3], s[4:5]
	s_cbranch_execz .LBB0_2422
	s_waitcnt lgkmcnt(0)
	v_add_f32_e32 v2, v2, v3
	ds_write_b32 v180, v2 offset:2816
